# batched loads: gemm_res/GLU epilogues, s5 carry loop, cbias, x-cvt, m2b prefetch; static setprio by wave slot
# speedup vs baseline: 1.0273x; 1.0273x over previous
; __global__ void __launch_bounds__(256, 2) mega(Params p, int ph_lo, int ph_hi) {
;     __shared__ __attribute__((aligned(16))) unsigned char smem[SMEM_BYTES];
;     __shared__ u32x4 xbw;
;     if (threadIdx.x == 0) xbw = (u32x4){0u, 0u, 0u, 0u};
_Z4mega6Paramsii:
	s_load_dwordx2 s[96:97], s[0:1], 0xe0
	s_load_dwordx8 s[4:11], s[0:1], 0xc0
	s_getreg_b32 s3, hwreg(HW_REG_HW_ID, 0, 4)
	s_and_b32 s3, s3, 1
	s_cmp_eq_u32 s3, 1
	s_cbranch_scc0 .Lprio_skip
	s_setprio 3
.Lprio_skip:
	v_and_b32_e32 v133, 0x3ff, v0
	s_waitcnt lgkmcnt(0)
	v_writelane_b32 v223, s4, 0
	s_nop 1
	v_writelane_b32 v223, s5, 1
	v_writelane_b32 v223, s6, 2
	v_writelane_b32 v223, s7, 3
	v_writelane_b32 v223, s8, 4
	v_writelane_b32 v223, s9, 5
	v_writelane_b32 v223, s10, 6
	v_writelane_b32 v223, s11, 7
	v_cmp_eq_u32_e64 s[6:7], 0, v133
	s_mov_b64 s[4:5], exec
	s_nop 0
	v_writelane_b32 v223, s6, 8
	s_nop 1
	v_writelane_b32 v223, s7, 9
	s_and_b64 s[6:7], s[4:5], s[6:7]
	s_mov_b64 exec, s[6:7]
	s_cbranch_execz .LBB0_2
	v_mov_b32_e32 v2, 0
	v_mov_b32_e32 v3, v2
	v_mov_b32_e32 v4, v2
	v_mov_b32_e32 v5, v2
	v_mov_b32_e32 v1, 0x12000
	ds_write_b128 v1, v[2:5]

; #define TIDX tid_()
; DEVI void compress_finish(const Params& p, int l, int kv, int t32, float* sm) {
;     ...
;     w2s = sm + 4160;
;     const int tid = TIDX;
; #pragma unroll
;     for (int i = 0; i < 8; ++i) *(f32x4*)(w2s + (i * 256 + tid) * 4) = *(const f32x4*)(w2 + (i * 256 + tid) * 4);
; #pragma unroll
;     for (int i = 0; i < 4; ++i) {
;         const int e = (i * 256 + tid) * 4, row = e >> 7, col = e & 127;
;         f32x4 v = *(const f32x4*)(bias + col);
; #pragma unroll
;         for (int sl = 1; sl < 8; ++sl) v += *(const f32x4*)(bias + sl * 128 + col);
; #pragma unroll
;         for (int ks = 0; ks < 4; ++ks) v += *(const f32x4*)(hp + (size_t)ks * 2 * 2048 * 128 + (size_t)row * 128 + col);
; #pragma unroll
;         for (int r = 0; r < 4; ++r) hid[row * 129 + col + r] = gelu_tanh(v[r]);
.LBB0_26:
	s_ashr_i32 s40, s17, 6
	s_lshl_b32 s26, s40, 10
	s_add_i32 s30, s26, s4
	s_and_b32 s22, s17, 63
	s_ashr_i32 s31, s30, 31
	s_cmp_gt_u32 s17, 63
	v_readlane_b32 s80, v223, 10
	s_cselect_b64 s[26:27], -1, 0
	s_cmp_lt_u32 s17, 64
	v_readlane_b32 s92, v223, 22
	v_readlane_b32 s44, v223, 26
	v_readlane_b32 s93, v223, 23
	v_readlane_b32 s45, v223, 27
	s_cselect_b32 s38, s92, s44
	v_mov_b32_e32 v14, v133
	s_cselect_b32 s28, s93, s45
	s_add_u32 s38, s38, s0
	s_addc_u32 s39, s28, s1
	v_lshlrev_b32_e32 v8, 2, v14
	v_ashrrev_i32_e32 v9, 31, v8
	v_lshl_add_u64 v[2:3], v[8:9], 2, s[38:39]
	v_add_u32_e32 v12, 0x400, v8
	v_lshlrev_b32_e32 v0, 4, v14
	v_ashrrev_i32_e32 v13, 31, v12
	v_add_u32_e32 v10, 0x800, v8
	v_ashrrev_i32_e32 v11, 31, v10
	s_ashr_i32 s41, s40, 31
	s_lshl_b64 s[40:41], s[40:41], 20
	s_add_u32 s28, s6, s40
	s_addc_u32 s40, s10, s41
	s_lshl_b64 s[30:31], s[30:31], 2
	s_add_u32 s30, s11, s30
	s_addc_u32 s31, s13, s31
	s_mov_b32 s7, 0x200000
	v_readlane_b32 s81, v223, 11
	v_readlane_b32 s82, v223, 12
	v_readlane_b32 s83, v223, 13
	v_readlane_b32 s84, v223, 14
	v_readlane_b32 s85, v223, 15
	v_readlane_b32 s86, v223, 16
	v_readlane_b32 s87, v223, 17
	v_readlane_b32 s88, v223, 18
	v_readlane_b32 s89, v223, 19
	v_readlane_b32 s90, v223, 20
	v_readlane_b32 s91, v223, 21
	v_readlane_b32 s94, v223, 24
	v_readlane_b32 s95, v223, 25
	v_readlane_b32 s46, v223, 28
	v_readlane_b32 s47, v223, 29
	v_readlane_b32 s48, v223, 30
	v_readlane_b32 s49, v223, 31
	v_readlane_b32 s50, v223, 32
	v_readlane_b32 s51, v223, 33
	v_readlane_b32 s52, v223, 34
	v_readlane_b32 s53, v223, 35
	v_readlane_b32 s54, v223, 36
	v_readlane_b32 s55, v223, 37
	v_readlane_b32 s56, v223, 38
	v_readlane_b32 s57, v223, 39
	v_readlane_b32 s58, v223, 40
	v_readlane_b32 s59, v223, 41
	v_lshlrev_b32_e32 v196, 2, v133
	v_mov_b32_e32 v197, 0
	v_lshl_add_u64 v[198:199], v[196:197], 2, s[38:39]
	v_add_u32_e32 v200, 0x400, v196
	v_mov_b32_e32 v201, 0
	v_lshl_add_u64 v[200:201], v[200:201], 2, s[38:39]
	v_lshl_add_u64 v[202:203], v[200:201], 0, s[36:37]
	v_lshl_add_u64 v[204:205], v[202:203], 0, s[36:37]
	v_lshl_add_u64 v[206:207], v[204:205], 0, s[36:37]
	global_load_dwordx4 v[40:43], v[198:199], off
	global_load_dwordx4 v[44:47], v[200:201], off
	global_load_dwordx4 v[48:51], v[202:203], off offset:-4096
	global_load_dwordx4 v[52:55], v[202:203], off
	global_load_dwordx4 v[56:59], v[204:205], off offset:-4096
	global_load_dwordx4 v[60:63], v[204:205], off
	global_load_dwordx4 v[64:67], v[206:207], off offset:-4096
	global_load_dwordx4 v[68:71], v[206:207], off
	v_lshlrev_b32_e32 v208, 4, v133
	v_and_b32_e32 v208, 0x1f0, v208
	global_load_dwordx4 v[72:75], v208, s[30:31]
	global_load_dwordx4 v[76:79], v208, s[30:31] offset:512
	global_load_dwordx4 v[80:83], v208, s[30:31] offset:1024
	global_load_dwordx4 v[84:87], v208, s[30:31] offset:1536
	global_load_dwordx4 v[88:91], v208, s[30:31] offset:2048
	global_load_dwordx4 v[92:95], v208, s[30:31] offset:2560
	global_load_dwordx4 v[96:99], v208, s[30:31] offset:3072
	global_load_dwordx4 v[100:103], v208, s[30:31] offset:3584
	v_mov_b32_e32 v210, s28
	v_mov_b32_e32 v211, s40
	v_mov_b32_e32 v212, s22
	v_lshlrev_b32_e32 v212, 14, v212
	v_mov_b32_e32 v213, 0
	v_lshl_add_u64 v[210:211], v[210:211], 0, v[212:213]
	v_mov_b32_e32 v209, 0
	v_lshl_add_u64 v[210:211], v[210:211], 0, v[208:209]
	v_lshrrev_b32_e32 v212, 5, v133
	v_lshlrev_b32_e32 v212, 9, v212
	v_lshl_add_u64 v[210:211], v[210:211], 0, v[212:213]
	v_mov_b32_e32 v214, 0x200000
	v_mov_b32_e32 v215, 0
	v_mov_b32_e32 v216, 0x1000
	v_mov_b32_e32 v217, 0
	global_load_dwordx4 v[104:107], v[210:211], off
	v_lshl_add_u64 v[218:219], v[210:211], 0, v[214:215]
	global_load_dwordx4 v[108:111], v[218:219], off
	v_lshl_add_u64 v[218:219], v[218:219], 0, v[214:215]
	global_load_dwordx4 v[112:115], v[218:219], off
	v_lshl_add_u64 v[218:219], v[218:219], 0, v[214:215]
	global_load_dwordx4 v[116:119], v[218:219], off
	v_lshl_add_u64 v[210:211], v[210:211], 0, v[216:217]
	global_load_dwordx4 v[120:123], v[210:211], off
	v_lshl_add_u64 v[218:219], v[210:211], 0, v[214:215]
	global_load_dwordx4 v[124:127], v[218:219], off
	v_lshl_add_u64 v[218:219], v[218:219], 0, v[214:215]
	global_load_dwordx4 v[128:131], v[218:219], off
	v_lshl_add_u64 v[218:219], v[218:219], 0, v[214:215]
	global_load_dwordx4 v[160:163], v[218:219], off
	v_lshl_add_u64 v[210:211], v[210:211], 0, v[216:217]
	global_load_dwordx4 v[164:167], v[210:211], off
	v_lshl_add_u64 v[218:219], v[210:211], 0, v[214:215]
	global_load_dwordx4 v[168:171], v[218:219], off
	v_lshl_add_u64 v[218:219], v[218:219], 0, v[214:215]
	global_load_dwordx4 v[172:175], v[218:219], off
	v_lshl_add_u64 v[218:219], v[218:219], 0, v[214:215]
	global_load_dwordx4 v[176:179], v[218:219], off
	v_lshl_add_u64 v[210:211], v[210:211], 0, v[216:217]
	global_load_dwordx4 v[180:183], v[210:211], off
	v_lshl_add_u64 v[218:219], v[210:211], 0, v[214:215]
	global_load_dwordx4 v[184:187], v[218:219], off
	v_lshl_add_u64 v[218:219], v[218:219], 0, v[214:215]
	global_load_dwordx4 v[188:191], v[218:219], off
	v_lshl_add_u64 v[218:219], v[218:219], 0, v[214:215]
	global_load_dwordx4 v[192:195], v[218:219], off
	s_waitcnt vmcnt(31)
	v_mov_b32_e32 v2, v40
	v_mov_b32_e32 v3, v41
	v_mov_b32_e32 v4, v42
	v_mov_b32_e32 v5, v43
	ds_write_b128 v0, v[2:5] offset:16640
	v_lshl_add_u64 v[2:3], v[12:13], 2, s[38:39]
	v_ashrrev_i32_e32 v12, 7, v12
	v_ashrrev_i32_e32 v13, 31, v12
	s_waitcnt vmcnt(30)
	v_mov_b32_e32 v2, v44
	v_mov_b32_e32 v3, v45
	v_mov_b32_e32 v4, v46
	v_mov_b32_e32 v5, v47
	ds_write_b128 v0, v[2:5] offset:20736
	v_lshl_add_u64 v[2:3], v[10:11], 2, s[38:39]
	s_waitcnt vmcnt(29)
; DEVI void compress_finish(const Params& p, int l, int kv, int t32, float* sm) {
;     ...
;     for (int i = 0; i < 8; ++i) *(f32x4*)(w2s + (i * 256 + tid) * 4) = *(const f32x4*)(w2 + (i * 256 + tid) * 4);
; #pragma unroll
;     for (int i = 0; i < 4; ++i) {
;         const int e = (i * 256 + tid) * 4, row = e >> 7, col = e & 127;
;         f32x4 v = *(const f32x4*)(bias + col);
; #pragma unroll
;         for (int sl = 1; sl < 8; ++sl) v += *(const f32x4*)(bias + sl * 128 + col);
; #pragma unroll
;         for (int ks = 0; ks < 4; ++ks) v += *(const f32x4*)(hp + (size_t)ks * 2 * 2048 * 128 + (size_t)row * 128 + col);
; #pragma unroll
;         for (int r = 0; r < 4; ++r) hid[row * 129 + col + r] = gelu_tanh(v[r]);
	v_mov_b32_e32 v2, v48
	v_mov_b32_e32 v3, v49
	v_mov_b32_e32 v4, v50
	v_mov_b32_e32 v5, v51
	ds_write_b128 v0, v[2:5] offset:24832
	v_add_u32_e32 v2, 0xc00, v8
	v_ashrrev_i32_e32 v3, 31, v2
	v_lshl_add_u64 v[4:5], v[2:3], 2, s[38:39]
	s_waitcnt vmcnt(28)
	v_mov_b32_e32 v4, v52
	v_mov_b32_e32 v5, v53
	v_mov_b32_e32 v6, v54
	v_mov_b32_e32 v7, v55
	ds_write_b128 v0, v[4:7] offset:28928
	v_add_u32_e32 v4, 0x1000, v8
	v_ashrrev_i32_e32 v5, 31, v4
	v_lshl_add_u64 v[4:5], v[4:5], 2, s[38:39]
	s_waitcnt vmcnt(27)
	v_mov_b32_e32 v4, v56
	v_mov_b32_e32 v5, v57
	v_mov_b32_e32 v6, v58
	v_mov_b32_e32 v7, v59
	ds_write_b128 v0, v[4:7] offset:33024
	v_add_u32_e32 v4, 0x1400, v8
	v_ashrrev_i32_e32 v5, 31, v4
	v_lshl_add_u64 v[4:5], v[4:5], 2, s[38:39]
	s_waitcnt vmcnt(26)
	v_mov_b32_e32 v4, v60
	v_mov_b32_e32 v5, v61
	v_mov_b32_e32 v6, v62
	v_mov_b32_e32 v7, v63
	ds_write_b128 v0, v[4:7] offset:37120
	v_add_u32_e32 v4, 0x1800, v8
	v_ashrrev_i32_e32 v5, 31, v4
	v_lshl_add_u64 v[4:5], v[4:5], 2, s[38:39]
	s_waitcnt vmcnt(25)
	v_mov_b32_e32 v4, v64
	v_mov_b32_e32 v5, v65
	v_mov_b32_e32 v6, v66
	v_mov_b32_e32 v7, v67
	ds_write_b128 v0, v[4:7] offset:41216
	v_add_u32_e32 v4, 0x1c00, v8
	v_ashrrev_i32_e32 v5, 31, v4
	v_lshl_add_u64 v[4:5], v[4:5], 2, s[38:39]
	s_lshl_b32 s38, s22, 14
	s_add_u32 s38, s28, s38
	s_addc_u32 s39, s40, 0
	s_movk_i32 s40, 0x204
	s_mov_b32 s28, 0
	s_waitcnt vmcnt(24)
	v_mov_b32_e32 v4, v68
	v_mov_b32_e32 v5, v69
	v_mov_b32_e32 v6, v70
	v_mov_b32_e32 v7, v71
	ds_write_b128 v0, v[4:7] offset:45312
	v_and_b32_e32 v0, 0x1f0, v0
	v_lshl_add_u64 v[4:5], s[38:39], 0, v[0:1]
	s_mov_b32 s38, 0x400000
	s_mov_b32 s39, 0x600000
	s_waitcnt vmcnt(22)
	v_mov_b32_e32 v6, v72
	v_mov_b32_e32 v7, v73
	v_mov_b32_e32 v8, v74
	v_mov_b32_e32 v9, v75
	v_mov_b32_e32 v16, v76
	v_mov_b32_e32 v17, v77
	v_mov_b32_e32 v18, v78
	v_mov_b32_e32 v19, v79
	v_pk_add_f32 v[18:19], v[8:9], v[18:19]
	v_pk_add_f32 v[16:17], v[6:7], v[16:17]
	s_waitcnt vmcnt(21)
	v_mov_b32_e32 v6, v80
	v_mov_b32_e32 v7, v81
	v_mov_b32_e32 v8, v82
	v_mov_b32_e32 v9, v83
	v_pk_add_f32 v[18:19], v[18:19], v[8:9]
	v_pk_add_f32 v[16:17], v[16:17], v[6:7]
	s_waitcnt vmcnt(20)
	v_mov_b32_e32 v6, v84
	v_mov_b32_e32 v7, v85
	v_mov_b32_e32 v8, v86
	v_mov_b32_e32 v9, v87
	v_pk_add_f32 v[18:19], v[18:19], v[8:9]
	v_pk_add_f32 v[16:17], v[16:17], v[6:7]
	s_waitcnt vmcnt(19)
	v_mov_b32_e32 v6, v88
	v_mov_b32_e32 v7, v89
	v_mov_b32_e32 v8, v90
	v_mov_b32_e32 v9, v91
	v_pk_add_f32 v[18:19], v[18:19], v[8:9]
	v_pk_add_f32 v[16:17], v[16:17], v[6:7]
	s_waitcnt vmcnt(18)
	v_mov_b32_e32 v6, v92
	v_mov_b32_e32 v7, v93
	v_mov_b32_e32 v8, v94
	v_mov_b32_e32 v9, v95
	v_pk_add_f32 v[18:19], v[18:19], v[8:9]
	v_pk_add_f32 v[16:17], v[16:17], v[6:7]
	s_waitcnt vmcnt(17)
	v_mov_b32_e32 v6, v96
	v_mov_b32_e32 v7, v97
	v_mov_b32_e32 v8, v98
	v_mov_b32_e32 v9, v99
	v_pk_add_f32 v[8:9], v[18:19], v[8:9]
	v_pk_add_f32 v[20:21], v[16:17], v[6:7]
	s_waitcnt vmcnt(16)
	v_mov_b32_e32 v16, v100
	v_mov_b32_e32 v17, v101
	v_mov_b32_e32 v18, v102
	v_mov_b32_e32 v19, v103
	v_pk_add_f32 v[6:7], v[8:9], v[18:19]
	v_pk_add_f32 v[8:9], v[20:21], v[16:17]
	v_bfe_i32 v20, v14, 5, 25
	v_ashrrev_i32_e32 v21, 31, v20
	v_lshlrev_b64 v[16:17], 9, v[20:21]
	v_lshl_add_u64 v[22:23], v[4:5], 0, v[16:17]
	v_mad_u64_u32 v[20:21], s[30:31], v20, s40, v[0:1]
	s_waitcnt vmcnt(15)
	v_mov_b32_e32 v16, v104
	v_mov_b32_e32 v17, v105
	v_mov_b32_e32 v18, v106
	v_mov_b32_e32 v19, v107
	v_pk_add_f32 v[26:27], v[8:9], v[16:17]
	v_add_co_u32_e32 v16, vcc, s7, v22
	v_pk_add_f32 v[24:25], v[6:7], v[18:19]
	s_nop 0
	v_addc_co_u32_e32 v17, vcc, 0, v23, vcc
	s_waitcnt vmcnt(14)
	v_mov_b32_e32 v16, v108
	v_mov_b32_e32 v17, v109
	v_mov_b32_e32 v18, v110
	v_mov_b32_e32 v19, v111
	v_pk_add_f32 v[26:27], v[26:27], v[16:17]
	v_add_co_u32_e32 v16, vcc, s38, v22
	v_pk_add_f32 v[24:25], v[24:25], v[18:19]
	s_nop 0
	v_addc_co_u32_e32 v17, vcc, 0, v23, vcc
	s_waitcnt vmcnt(13)
	v_mov_b32_e32 v16, v112
	v_mov_b32_e32 v17, v113
	v_mov_b32_e32 v18, v114
	v_mov_b32_e32 v19, v115
	v_pk_add_f32 v[26:27], v[26:27], v[16:17]
	v_add_co_u32_e32 v16, vcc, s39, v22
	v_pk_add_f32 v[24:25], v[24:25], v[18:19]
	s_nop 0
	v_addc_co_u32_e32 v17, vcc, 0, v23, vcc
	s_waitcnt vmcnt(12)
	v_mov_b32_e32 v16, v116
	v_mov_b32_e32 v17, v117
	v_mov_b32_e32 v18, v118
	v_mov_b32_e32 v19, v119
	v_pk_add_f32 v[16:17], v[26:27], v[16:17]
	s_nop 0
	v_mul_f32_e32 v3, 0x3d372713, v16
	v_mul_f32_e32 v3, v16, v3
	v_fma_f32 v3, v16, v3, v16
	v_mul_f32_e32 v3, 0x3f4c422a, v3
	v_mul_f32_e32 v3, 0x4038aa3b, v3
	v_exp_f32_e32 v3, v3
	v_pk_add_f32 v[18:19], v[24:25], v[18:19]
	v_add_f32_e32 v3, 1.0, v3
	v_rcp_f32_e32 v22, v3
	v_mul_f32_e32 v3, 0x3d372713, v17
	v_mul_f32_e32 v3, v17, v3
	v_fma_f32 v3, v17, v3, v17
	v_mul_f32_e32 v3, 0x3f4c422a, v3
	v_mul_f32_e32 v3, 0x4038aa3b, v3
	v_exp_f32_e32 v3, v3
	v_pk_mul_f32 v[16:17], v[16:17], 0.5 op_sel_hi:[1,0]
	v_add_f32_e32 v3, 1.0, v3
	v_rcp_f32_e32 v23, v3
	v_mul_f32_e32 v3, 0x3d372713, v18
	v_mul_f32_e32 v3, v18, v3
	v_fma_f32 v3, v18, v3, v18
	v_mul_f32_e32 v3, 0x3f4c422a, v3
	v_mul_f32_e32 v3, 0x4038aa3b, v3
	v_exp_f32_e32 v3, v3
	v_pk_fma_f32 v[22:23], v[22:23], 2.0, 1.0 op_sel_hi:[1,0,0] neg_lo:[1,0,0] neg_hi:[1,0,0]
	v_add_f32_e32 v3, 1.0, v3
	v_pk_add_f32 v[22:23], v[22:23], 1.0 op_sel_hi:[1,0]
	s_nop 0
	v_pk_mul_f32 v[16:17], v[16:17], v[22:23]
	ds_write2_b32 v20, v16, v17 offset1:1
	v_rcp_f32_e32 v16, v3
	v_mul_f32_e32 v3, 0x3d372713, v19
	v_mul_f32_e32 v3, v19, v3
	v_fma_f32 v3, v19, v3, v19
	v_mul_f32_e32 v3, 0x3f4c422a, v3
	v_mul_f32_e32 v3, 0x4038aa3b, v3
	v_exp_f32_e32 v3, v3
	v_pk_mul_f32 v[18:19], v[18:19], 0.5 op_sel_hi:[1,0]
	v_add_f32_e32 v3, 1.0, v3
	v_rcp_f32_e32 v17, v3
	s_nop 0
	v_pk_fma_f32 v[16:17], v[16:17], 2.0, 1.0 op_sel_hi:[1,0,0] neg_lo:[1,0,0] neg_hi:[1,0,0]
	s_nop 0
	v_pk_add_f32 v[16:17], v[16:17], 1.0 op_sel_hi:[1,0]
	s_nop 0
	v_pk_mul_f32 v[16:17], v[18:19], v[16:17]
	ds_write2_b32 v20, v16, v17 offset0:2 offset1:3
	v_lshlrev_b64 v[16:17], 9, v[12:13]
	v_lshl_add_u64 v[20:21], v[4:5], 0, v[16:17]
	v_mad_u64_u32 v[12:13], s[30:31], v12, s40, v[0:1]
	s_waitcnt vmcnt(11)
; DEVI void compress_finish(const Params& p, int l, int kv, int t32, float* sm) {
;     ...
;     for (int i = 0; i < 4; ++i) {
;         const int e = (i * 256 + tid) * 4, row = e >> 7, col = e & 127;
;         f32x4 v = *(const f32x4*)(bias + col);
; #pragma unroll
;         for (int sl = 1; sl < 8; ++sl) v += *(const f32x4*)(bias + sl * 128 + col);
; #pragma unroll
;         for (int ks = 0; ks < 4; ++ks) v += *(const f32x4*)(hp + (size_t)ks * 2 * 2048 * 128 + (size_t)row * 128 + col);
; #pragma unroll
;         for (int r = 0; r < 4; ++r) hid[row * 129 + col + r] = gelu_tanh(v[r]);
	v_mov_b32_e32 v16, v120
	v_mov_b32_e32 v17, v121
	v_mov_b32_e32 v18, v122
	v_mov_b32_e32 v19, v123
	v_pk_add_f32 v[24:25], v[8:9], v[16:17]
	v_add_co_u32_e32 v16, vcc, s7, v20
	v_pk_add_f32 v[22:23], v[6:7], v[18:19]
	s_nop 0
	v_addc_co_u32_e32 v17, vcc, 0, v21, vcc
	s_waitcnt vmcnt(10)
	v_mov_b32_e32 v16, v124
	v_mov_b32_e32 v17, v125
	v_mov_b32_e32 v18, v126
	v_mov_b32_e32 v19, v127
	v_pk_add_f32 v[24:25], v[24:25], v[16:17]
	v_add_co_u32_e32 v16, vcc, s38, v20
	v_pk_add_f32 v[22:23], v[22:23], v[18:19]
	s_nop 0
	v_addc_co_u32_e32 v17, vcc, 0, v21, vcc
	s_waitcnt vmcnt(9)
	v_mov_b32_e32 v16, v128
	v_mov_b32_e32 v17, v129
	v_mov_b32_e32 v18, v130
	v_mov_b32_e32 v19, v131
	v_pk_add_f32 v[24:25], v[24:25], v[16:17]
	v_add_co_u32_e32 v16, vcc, s39, v20
	v_pk_add_f32 v[22:23], v[22:23], v[18:19]
	s_nop 0
	v_addc_co_u32_e32 v17, vcc, 0, v21, vcc
	s_waitcnt vmcnt(8)
	v_mov_b32_e32 v16, v160
	v_mov_b32_e32 v17, v161
	v_mov_b32_e32 v18, v162
	v_mov_b32_e32 v19, v163
	v_pk_add_f32 v[16:17], v[24:25], v[16:17]
	s_nop 0
	v_mul_f32_e32 v3, 0x3d372713, v16
	v_mul_f32_e32 v3, v16, v3
	v_fma_f32 v3, v16, v3, v16
	v_mul_f32_e32 v3, 0x3f4c422a, v3
	v_mul_f32_e32 v3, 0x4038aa3b, v3
	v_exp_f32_e32 v3, v3
	v_pk_add_f32 v[18:19], v[22:23], v[18:19]
	v_add_f32_e32 v3, 1.0, v3
	v_rcp_f32_e32 v20, v3
	v_mul_f32_e32 v3, 0x3d372713, v17
	v_mul_f32_e32 v3, v17, v3
	v_fma_f32 v3, v17, v3, v17
	v_mul_f32_e32 v3, 0x3f4c422a, v3
	v_mul_f32_e32 v3, 0x4038aa3b, v3
	v_exp_f32_e32 v3, v3
	v_pk_mul_f32 v[16:17], v[16:17], 0.5 op_sel_hi:[1,0]
	v_add_f32_e32 v3, 1.0, v3
	v_rcp_f32_e32 v21, v3
	v_mul_f32_e32 v3, 0x3d372713, v18
	v_mul_f32_e32 v3, v18, v3
	v_fma_f32 v3, v18, v3, v18
	v_mul_f32_e32 v3, 0x3f4c422a, v3
	v_mul_f32_e32 v3, 0x4038aa3b, v3
	v_exp_f32_e32 v3, v3
	v_pk_fma_f32 v[20:21], v[20:21], 2.0, 1.0 op_sel_hi:[1,0,0] neg_lo:[1,0,0] neg_hi:[1,0,0]
	v_add_f32_e32 v3, 1.0, v3
	v_pk_add_f32 v[20:21], v[20:21], 1.0 op_sel_hi:[1,0]
	s_nop 0
	v_pk_mul_f32 v[16:17], v[16:17], v[20:21]
	ds_write2_b32 v12, v16, v17 offset1:1
	v_rcp_f32_e32 v16, v3
	v_mul_f32_e32 v3, 0x3d372713, v19
	v_mul_f32_e32 v3, v19, v3
	v_fma_f32 v3, v19, v3, v19
	v_mul_f32_e32 v3, 0x3f4c422a, v3
	v_mul_f32_e32 v3, 0x4038aa3b, v3
	v_exp_f32_e32 v3, v3
	v_pk_mul_f32 v[18:19], v[18:19], 0.5 op_sel_hi:[1,0]
	v_add_f32_e32 v3, 1.0, v3
	v_rcp_f32_e32 v17, v3
	s_nop 0
	v_pk_fma_f32 v[16:17], v[16:17], 2.0, 1.0 op_sel_hi:[1,0,0] neg_lo:[1,0,0] neg_hi:[1,0,0]
	s_nop 0
	v_pk_add_f32 v[16:17], v[16:17], 1.0 op_sel_hi:[1,0]
	s_nop 0
	v_pk_mul_f32 v[16:17], v[18:19], v[16:17]
	ds_write2_b32 v12, v16, v17 offset0:2 offset1:3
	v_ashrrev_i32_e32 v16, 7, v10
	v_ashrrev_i32_e32 v17, 31, v16
	v_lshlrev_b64 v[10:11], 9, v[16:17]
	v_lshl_add_u64 v[18:19], v[4:5], 0, v[10:11]
	v_mad_u64_u32 v[16:17], s[30:31], v16, s40, v[0:1]
	s_waitcnt vmcnt(7)
	v_mov_b32_e32 v10, v164
	v_mov_b32_e32 v11, v165
	v_mov_b32_e32 v12, v166
	v_mov_b32_e32 v13, v167
	v_pk_add_f32 v[22:23], v[8:9], v[10:11]
	v_add_co_u32_e32 v10, vcc, s7, v18
	v_pk_add_f32 v[20:21], v[6:7], v[12:13]
	s_nop 0
	v_addc_co_u32_e32 v11, vcc, 0, v19, vcc
	s_waitcnt vmcnt(6)
	v_mov_b32_e32 v10, v168
	v_mov_b32_e32 v11, v169
	v_mov_b32_e32 v12, v170
	v_mov_b32_e32 v13, v171
	v_pk_add_f32 v[22:23], v[22:23], v[10:11]
	v_add_co_u32_e32 v10, vcc, s38, v18
	v_pk_add_f32 v[20:21], v[20:21], v[12:13]
	s_nop 0
	v_addc_co_u32_e32 v11, vcc, 0, v19, vcc
	s_waitcnt vmcnt(5)
	v_mov_b32_e32 v10, v172
	v_mov_b32_e32 v11, v173
	v_mov_b32_e32 v12, v174
	v_mov_b32_e32 v13, v175
	v_pk_add_f32 v[22:23], v[22:23], v[10:11]
	v_add_co_u32_e32 v10, vcc, s39, v18
	v_pk_add_f32 v[20:21], v[20:21], v[12:13]
	s_nop 0
	v_addc_co_u32_e32 v11, vcc, 0, v19, vcc
	s_waitcnt vmcnt(4)
; DEVI void compress_finish(const Params& p, int l, int kv, int t32, float* sm) {
;     ...
;     for (int i = 0; i < 4; ++i) {
;         const int e = (i * 256 + tid) * 4, row = e >> 7, col = e & 127;
;         f32x4 v = *(const f32x4*)(bias + col);
; #pragma unroll
;         for (int sl = 1; sl < 8; ++sl) v += *(const f32x4*)(bias + sl * 128 + col);
; #pragma unroll
;         for (int ks = 0; ks < 4; ++ks) v += *(const f32x4*)(hp + (size_t)ks * 2 * 2048 * 128 + (size_t)row * 128 + col);
; #pragma unroll
;         for (int r = 0; r < 4; ++r) hid[row * 129 + col + r] = gelu_tanh(v[r]);
;     }
;     __syncthreads();
;     {
;         const int d = tid & 63, rq = tid >> 6;
;         float o[8];
; #pragma unroll
;         for (int i = 0; i < 8; ++i) o[i] = 0.f;
	v_mov_b32_e32 v10, v176
	v_mov_b32_e32 v11, v177
	v_mov_b32_e32 v12, v178
	v_mov_b32_e32 v13, v179
	v_pk_add_f32 v[10:11], v[22:23], v[10:11]
	s_nop 0
	v_mul_f32_e32 v3, 0x3d372713, v10
	v_mul_f32_e32 v3, v10, v3
	v_fma_f32 v3, v10, v3, v10
	v_mul_f32_e32 v3, 0x3f4c422a, v3
	v_mul_f32_e32 v3, 0x4038aa3b, v3
	v_exp_f32_e32 v3, v3
	v_pk_add_f32 v[12:13], v[20:21], v[12:13]
	v_add_f32_e32 v3, 1.0, v3
	v_rcp_f32_e32 v18, v3
	v_mul_f32_e32 v3, 0x3d372713, v11
	v_mul_f32_e32 v3, v11, v3
	v_fma_f32 v3, v11, v3, v11
	v_mul_f32_e32 v3, 0x3f4c422a, v3
	v_mul_f32_e32 v3, 0x4038aa3b, v3
	v_exp_f32_e32 v3, v3
	v_pk_mul_f32 v[10:11], v[10:11], 0.5 op_sel_hi:[1,0]
	v_add_f32_e32 v3, 1.0, v3
	v_rcp_f32_e32 v19, v3
	v_mul_f32_e32 v3, 0x3d372713, v12
	v_mul_f32_e32 v3, v12, v3
	v_fma_f32 v3, v12, v3, v12
	v_mul_f32_e32 v3, 0x3f4c422a, v3
	v_mul_f32_e32 v3, 0x4038aa3b, v3
	v_exp_f32_e32 v3, v3
	v_pk_fma_f32 v[18:19], v[18:19], 2.0, 1.0 op_sel_hi:[1,0,0] neg_lo:[1,0,0] neg_hi:[1,0,0]
	v_add_f32_e32 v3, 1.0, v3
	v_pk_add_f32 v[18:19], v[18:19], 1.0 op_sel_hi:[1,0]
	s_nop 0
	v_pk_mul_f32 v[10:11], v[10:11], v[18:19]
	ds_write2_b32 v16, v10, v11 offset1:1
	v_rcp_f32_e32 v10, v3
	v_mul_f32_e32 v3, 0x3d372713, v13
	v_mul_f32_e32 v3, v13, v3
	v_fma_f32 v3, v13, v3, v13
	v_mul_f32_e32 v3, 0x3f4c422a, v3
	v_mul_f32_e32 v3, 0x4038aa3b, v3
	v_exp_f32_e32 v3, v3
	v_pk_mul_f32 v[12:13], v[12:13], 0.5 op_sel_hi:[1,0]
	v_add_f32_e32 v3, 1.0, v3
	v_rcp_f32_e32 v11, v3
	s_nop 0
	v_pk_fma_f32 v[10:11], v[10:11], 2.0, 1.0 op_sel_hi:[1,0,0] neg_lo:[1,0,0] neg_hi:[1,0,0]
	s_nop 0
	v_pk_add_f32 v[10:11], v[10:11], 1.0 op_sel_hi:[1,0]
	s_nop 0
	v_pk_mul_f32 v[10:11], v[12:13], v[10:11]
	ds_write2_b32 v16, v10, v11 offset0:2 offset1:3
	v_ashrrev_i32_e32 v10, 7, v2
	v_ashrrev_i32_e32 v11, 31, v10
	v_lshlrev_b64 v[2:3], 9, v[10:11]
	v_lshl_add_u64 v[12:13], v[4:5], 0, v[2:3]
	v_and_b32_e32 v11, 63, v14
	s_waitcnt vmcnt(3)
	v_mov_b32_e32 v2, v180
	v_mov_b32_e32 v3, v181
	v_mov_b32_e32 v4, v182
	v_mov_b32_e32 v5, v183
	v_pk_add_f32 v[8:9], v[8:9], v[2:3]
	v_add_co_u32_e32 v2, vcc, s7, v12
	v_pk_add_f32 v[6:7], v[6:7], v[4:5]
	s_nop 0
	v_addc_co_u32_e32 v3, vcc, 0, v13, vcc
	s_waitcnt vmcnt(2)
	v_mov_b32_e32 v2, v184
	v_mov_b32_e32 v3, v185
	v_mov_b32_e32 v4, v186
	v_mov_b32_e32 v5, v187
	v_pk_add_f32 v[8:9], v[8:9], v[2:3]
	v_add_co_u32_e32 v2, vcc, s38, v12
	v_pk_add_f32 v[6:7], v[6:7], v[4:5]
	s_nop 0
	v_addc_co_u32_e32 v3, vcc, 0, v13, vcc
	s_waitcnt vmcnt(1)
	v_mov_b32_e32 v2, v188
	v_mov_b32_e32 v3, v189
	v_mov_b32_e32 v4, v190
	v_mov_b32_e32 v5, v191
	v_pk_add_f32 v[16:17], v[6:7], v[4:5]
	v_pk_add_f32 v[4:5], v[8:9], v[2:3]
	v_add_co_u32_e32 v2, vcc, s39, v12
	s_nop 1
	v_addc_co_u32_e32 v3, vcc, 0, v13, vcc
	v_lshl_or_b32 v13, v11, 2, v150
	s_waitcnt vmcnt(0)
	v_mov_b32_e32 v6, v192
	v_mov_b32_e32 v7, v193
	v_mov_b32_e32 v8, v194
	v_mov_b32_e32 v9, v195
	v_pk_add_f32 v[4:5], v[4:5], v[6:7]
	v_mad_u64_u32 v[6:7], s[30:31], v10, s40, v[0:1]
	v_mul_f32_e32 v0, 0x3d372713, v4
	v_mul_f32_e32 v0, v4, v0
	v_fma_f32 v0, v4, v0, v4
	v_mul_f32_e32 v0, 0x3f4c422a, v0
	v_mul_f32_e32 v0, 0x4038aa3b, v0
	v_exp_f32_e32 v0, v0
	v_pk_add_f32 v[2:3], v[16:17], v[8:9]
	v_add_f32_e32 v0, 1.0, v0
	v_rcp_f32_e32 v8, v0
	v_mul_f32_e32 v0, 0x3d372713, v5
	v_mul_f32_e32 v0, v5, v0
	v_fma_f32 v0, v5, v0, v5
	v_mul_f32_e32 v0, 0x3f4c422a, v0
	v_mul_f32_e32 v0, 0x4038aa3b, v0
	v_exp_f32_e32 v0, v0
	v_pk_mul_f32 v[4:5], v[4:5], 0.5 op_sel_hi:[1,0]
	v_add_f32_e32 v0, 1.0, v0
	v_rcp_f32_e32 v9, v0
	v_mul_f32_e32 v0, 0x3d372713, v2
	v_mul_f32_e32 v0, v2, v0
	v_fma_f32 v0, v2, v0, v2
	v_mul_f32_e32 v0, 0x3f4c422a, v0
	v_mul_f32_e32 v0, 0x4038aa3b, v0
	v_exp_f32_e32 v0, v0
	v_pk_fma_f32 v[8:9], v[8:9], 2.0, 1.0 op_sel_hi:[1,0,0] neg_lo:[1,0,0] neg_hi:[1,0,0]
	v_add_f32_e32 v0, 1.0, v0
	v_pk_add_f32 v[8:9], v[8:9], 1.0 op_sel_hi:[1,0]
	s_nop 0
	v_pk_mul_f32 v[4:5], v[4:5], v[8:9]
	ds_write2_b32 v6, v4, v5 offset1:1
	v_rcp_f32_e32 v4, v0
	v_mul_f32_e32 v0, 0x3d372713, v3
	v_mul_f32_e32 v0, v3, v0
	v_fma_f32 v0, v3, v0, v3
	v_mul_f32_e32 v0, 0x3f4c422a, v0
	v_mul_f32_e32 v0, 0x4038aa3b, v0
	v_exp_f32_e32 v0, v0
	v_pk_mul_f32 v[2:3], v[2:3], 0.5 op_sel_hi:[1,0]
	v_mov_b32_e32 v8, 0
	v_mov_b32_e32 v9, v8
	v_add_f32_e32 v0, 1.0, v0
	v_rcp_f32_e32 v5, v0
	v_mov_b32_e32 v7, v8
	v_pk_fma_f32 v[4:5], v[4:5], 2.0, 1.0 op_sel_hi:[1,0,0] neg_lo:[1,0,0] neg_hi:[1,0,0]
	s_nop 0
	v_pk_add_f32 v[4:5], v[4:5], 1.0 op_sel_hi:[1,0]
	s_nop 0
	v_pk_mul_f32 v[2:3], v[2:3], v[4:5]
	ds_write2_b32 v6, v2, v3 offset0:2 offset1:3
	v_ashrrev_i32_e32 v2, 3, v14
	v_and_b32_e32 v0, -8, v2
	v_or_b32_e32 v2, 7, v2
	v_mul_lo_u32 v10, v0, s40
	v_mul_lo_u32 v12, v2, s40
	v_mov_b32_e32 v6, v8
	v_mov_b32_e32 v4, v8
	v_mov_b32_e32 v5, v8
	v_mov_b32_e32 v2, v8
	v_mov_b32_e32 v3, v8
	s_waitcnt lgkmcnt(0)
	s_barrier

; DEVI void phase_gemm_res(const Params& p, const bf16_t* A, int K, const bf16_t* Bt, const float* xraw, int lnidx, float bscale, bf16_t* smem) {
;     ...
;             f32x4 g4[4], b4[4];
; #pragma unroll
;             for (int ni = 0; ni < 4; ++ni) {
;                 const int col = tn * 128 + wc * 64 + ni * 16 + quad * 4;
;                 g4[ni] = *(const f32x4*)(lg + col) * ALPHA; b4[ni] = *(const f32x4*)(lb + col) * ALPHA;
;             }
; #pragma unroll
;             for (int mi = 0; mi < 4; ++mi) {
;                 const int row = tm * 128 + wr * 64 + mi * 16 + l16;
;                 const f32x2v st = stats[row];
; #pragma unroll
;                 for (int ni = 0; ni < 4; ++ni) {
;                     const size_t idx = (size_t)row * D_ + tn * 128 + wc * 64 + ni * 16 + quad * 4;
;                     const f32x4 rv = *(const f32x4*)(hbuf + idx);
;                     *(f32x4*)(hbuf + idx) = ((rv - st[0]) * st[1]) * g4[ni] + b4[ni] + acc[mi][ni] * bscale;
;                 }
;             }
.LBB0_207:
	s_lshl_b32 s46, s46, 7
	s_ashr_i32 s47, s46, 31
	v_or_b32_e32 v210, s46, v105
	v_lshl_add_u32 v70, s42, 7, v104
	v_ashrrev_i32_e32 v211, 31, v210
	v_lshlrev_b64 v[210:211], 2, v[210:211]
	v_lshl_add_u64 v[206:207], s[24:25], 0, v[210:211]
	v_lshl_add_u64 v[208:209], s[26:27], 0, v[210:211]
	v_ashrrev_i32_e32 v71, 31, v70
	global_load_dwordx4 v[72:75], v[206:207], off
	global_load_dwordx4 v[76:79], v[206:207], off offset:64
	global_load_dwordx4 v[80:83], v[206:207], off offset:128
	global_load_dwordx4 v[84:87], v[206:207], off offset:192
	global_load_dwordx4 v[88:91], v[208:209], off
	global_load_dwordx4 v[92:95], v[208:209], off offset:64
	global_load_dwordx4 v[96:99], v[208:209], off offset:128
	global_load_dwordx4 v[100:103], v[208:209], off offset:192
	v_lshl_add_u64 v[210:211], v[70:71], 3, s[14:15]
	global_load_dwordx2 v[106:107], v[210:211], off
	global_load_dwordx2 v[108:109], v[210:211], off offset:128
	global_load_dwordx2 v[110:111], v[210:211], off offset:256
	global_load_dwordx2 v[140:141], v[210:211], off offset:384
	v_lshl_add_u64 v[212:213], s[46:47], 2, v[66:67]
	v_lshlrev_b64 v[214:215], 12, v[70:71]
	v_lshl_add_u64 v[128:129], v[212:213], 0, v[214:215]
	s_mov_b64 s[46:47], 0x10000
	v_lshl_add_u64 v[130:131], v[128:129], 0, s[46:47]
	v_lshl_add_u64 v[134:135], v[130:131], 0, s[46:47]
	v_lshl_add_u64 v[138:139], v[134:135], 0, s[46:47]
	global_load_dwordx4 v[112:115], v[128:129], off
	global_load_dwordx4 v[116:119], v[128:129], off offset:64
	global_load_dwordx4 v[120:123], v[128:129], off offset:128
	global_load_dwordx4 v[124:127], v[128:129], off offset:192
	global_load_dwordx4 v[160:163], v[130:131], off
	global_load_dwordx4 v[164:167], v[130:131], off offset:64
	global_load_dwordx4 v[168:171], v[130:131], off offset:128
	global_load_dwordx4 v[172:175], v[130:131], off offset:192
	global_load_dwordx4 v[176:179], v[134:135], off
	global_load_dwordx4 v[180:183], v[134:135], off offset:64
	global_load_dwordx4 v[184:187], v[134:135], off offset:128
	global_load_dwordx4 v[188:191], v[134:135], off offset:192
	global_load_dwordx4 v[192:195], v[138:139], off
	global_load_dwordx4 v[196:199], v[138:139], off offset:64
	global_load_dwordx4 v[200:203], v[138:139], off offset:128
	global_load_dwordx4 v[216:219], v[138:139], off offset:192
	s_waitcnt vmcnt(16)
	v_pk_mul_f32 v[72:73], v[72:73], s[20:21] op_sel_hi:[1,0]
	v_pk_mul_f32 v[74:75], v[74:75], s[20:21] op_sel_hi:[1,0]
	v_pk_mul_f32 v[88:89], v[88:89], s[20:21] op_sel_hi:[1,0]
	v_pk_mul_f32 v[90:91], v[90:91], s[20:21] op_sel_hi:[1,0]
	v_pk_mul_f32 v[76:77], v[76:77], s[20:21] op_sel_hi:[1,0]
	v_pk_mul_f32 v[78:79], v[78:79], s[20:21] op_sel_hi:[1,0]
	v_pk_mul_f32 v[92:93], v[92:93], s[20:21] op_sel_hi:[1,0]
	v_pk_mul_f32 v[94:95], v[94:95], s[20:21] op_sel_hi:[1,0]
	v_pk_mul_f32 v[80:81], v[80:81], s[20:21] op_sel_hi:[1,0]
	v_pk_mul_f32 v[82:83], v[82:83], s[20:21] op_sel_hi:[1,0]
	v_pk_mul_f32 v[96:97], v[96:97], s[20:21] op_sel_hi:[1,0]
	v_pk_mul_f32 v[98:99], v[98:99], s[20:21] op_sel_hi:[1,0]
	v_pk_mul_f32 v[84:85], v[84:85], s[20:21] op_sel_hi:[1,0]
	v_pk_mul_f32 v[86:87], v[86:87], s[20:21] op_sel_hi:[1,0]
	v_pk_mul_f32 v[100:101], v[100:101], s[20:21] op_sel_hi:[1,0]
	v_pk_mul_f32 v[102:103], v[102:103], s[20:21] op_sel_hi:[1,0]
	s_waitcnt vmcnt(15)
	v_sub_f32_e32 v113, v113, v106
	v_sub_f32_e32 v112, v112, v106
	v_sub_f32_e32 v115, v115, v106
	v_sub_f32_e32 v114, v114, v106
	v_pk_mul_f32 v[114:115], v[106:107], v[114:115] op_sel:[1,0]
	v_pk_mul_f32 v[112:113], v[106:107], v[112:113] op_sel:[1,0]
	v_pk_fma_f32 v[114:115], v[74:75], v[114:115], v[90:91]
	v_pk_fma_f32 v[112:113], v[72:73], v[112:113], v[88:89]
	v_pk_add_f32 v[64:65], v[64:65], v[114:115]
	v_pk_add_f32 v[62:63], v[62:63], v[112:113]
	global_store_dwordx4 v[128:129], v[62:65], off
	s_waitcnt vmcnt(15)
	v_sub_f32_e32 v117, v117, v106
	v_sub_f32_e32 v116, v116, v106
	v_sub_f32_e32 v119, v119, v106
	v_sub_f32_e32 v118, v118, v106
	v_pk_mul_f32 v[118:119], v[106:107], v[118:119] op_sel:[1,0]
	v_pk_mul_f32 v[116:117], v[106:107], v[116:117] op_sel:[1,0]
	v_pk_fma_f32 v[118:119], v[78:79], v[118:119], v[94:95]
	v_pk_fma_f32 v[116:117], v[76:77], v[116:117], v[92:93]
	v_pk_add_f32 v[60:61], v[60:61], v[118:119]
	v_pk_add_f32 v[58:59], v[58:59], v[116:117]
	global_store_dwordx4 v[128:129], v[58:61], off offset:64
	s_waitcnt vmcnt(15)
	v_sub_f32_e32 v121, v121, v106
	v_sub_f32_e32 v120, v120, v106
	v_sub_f32_e32 v123, v123, v106
	v_sub_f32_e32 v122, v122, v106
	v_pk_mul_f32 v[122:123], v[106:107], v[122:123] op_sel:[1,0]
	v_pk_mul_f32 v[120:121], v[106:107], v[120:121] op_sel:[1,0]
	v_pk_fma_f32 v[122:123], v[82:83], v[122:123], v[98:99]
	v_pk_fma_f32 v[120:121], v[80:81], v[120:121], v[96:97]
	v_pk_add_f32 v[56:57], v[56:57], v[122:123]
	v_pk_add_f32 v[54:55], v[54:55], v[120:121]
	global_store_dwordx4 v[128:129], v[54:57], off offset:128
	s_waitcnt vmcnt(15)
	v_sub_f32_e32 v125, v125, v106
	v_sub_f32_e32 v124, v124, v106
	v_sub_f32_e32 v127, v127, v106
	v_sub_f32_e32 v126, v126, v106
	v_pk_mul_f32 v[126:127], v[106:107], v[126:127] op_sel:[1,0]
	v_pk_mul_f32 v[124:125], v[106:107], v[124:125] op_sel:[1,0]
	v_pk_fma_f32 v[126:127], v[86:87], v[126:127], v[102:103]
	v_pk_fma_f32 v[124:125], v[84:85], v[124:125], v[100:101]
	v_pk_add_f32 v[52:53], v[52:53], v[126:127]
	v_pk_add_f32 v[50:51], v[50:51], v[124:125]
	global_store_dwordx4 v[128:129], v[50:53], off offset:192
	s_waitcnt vmcnt(15)
; DEVI void phase_gemm_res(const Params& p, const bf16_t* A, int K, const bf16_t* Bt, const float* xraw, int lnidx, float bscale, bf16_t* smem) {
;     ...
; #pragma unroll
;             for (int mi = 0; mi < 4; ++mi) {
;                 const int row = tm * 128 + wr * 64 + mi * 16 + l16;
;                 const f32x2v st = stats[row];
; #pragma unroll
;                 for (int ni = 0; ni < 4; ++ni) {
;                     const size_t idx = (size_t)row * D_ + tn * 128 + wc * 64 + ni * 16 + quad * 4;
;                     const f32x4 rv = *(const f32x4*)(hbuf + idx);
;                     *(f32x4*)(hbuf + idx) = ((rv - st[0]) * st[1]) * g4[ni] + b4[ni] + acc[mi][ni] * bscale;
;                 }
;             }
	v_sub_f32_e32 v161, v161, v108
	v_sub_f32_e32 v160, v160, v108
	v_sub_f32_e32 v163, v163, v108
	v_sub_f32_e32 v162, v162, v108
	v_pk_mul_f32 v[162:163], v[108:109], v[162:163] op_sel:[1,0]
	v_pk_mul_f32 v[160:161], v[108:109], v[160:161] op_sel:[1,0]
	v_pk_fma_f32 v[162:163], v[74:75], v[162:163], v[90:91]
	v_pk_fma_f32 v[160:161], v[72:73], v[160:161], v[88:89]
	v_pk_add_f32 v[48:49], v[48:49], v[162:163]
	v_pk_add_f32 v[46:47], v[46:47], v[160:161]
	global_store_dwordx4 v[130:131], v[46:49], off
	s_waitcnt vmcnt(15)
	v_sub_f32_e32 v165, v165, v108
	v_sub_f32_e32 v164, v164, v108
	v_sub_f32_e32 v167, v167, v108
	v_sub_f32_e32 v166, v166, v108
	v_pk_mul_f32 v[166:167], v[108:109], v[166:167] op_sel:[1,0]
	v_pk_mul_f32 v[164:165], v[108:109], v[164:165] op_sel:[1,0]
	v_pk_fma_f32 v[166:167], v[78:79], v[166:167], v[94:95]
	v_pk_fma_f32 v[164:165], v[76:77], v[164:165], v[92:93]
	v_pk_add_f32 v[44:45], v[44:45], v[166:167]
	v_pk_add_f32 v[42:43], v[42:43], v[164:165]
	global_store_dwordx4 v[130:131], v[42:45], off offset:64
	s_waitcnt vmcnt(15)
	v_sub_f32_e32 v169, v169, v108
	v_sub_f32_e32 v168, v168, v108
	v_sub_f32_e32 v171, v171, v108
	v_sub_f32_e32 v170, v170, v108
	v_pk_mul_f32 v[170:171], v[108:109], v[170:171] op_sel:[1,0]
	v_pk_mul_f32 v[168:169], v[108:109], v[168:169] op_sel:[1,0]
	v_pk_fma_f32 v[170:171], v[82:83], v[170:171], v[98:99]
	v_pk_fma_f32 v[168:169], v[80:81], v[168:169], v[96:97]
	v_pk_add_f32 v[40:41], v[40:41], v[170:171]
	v_pk_add_f32 v[38:39], v[38:39], v[168:169]
	global_store_dwordx4 v[130:131], v[38:41], off offset:128
	s_waitcnt vmcnt(15)
	v_sub_f32_e32 v173, v173, v108
	v_sub_f32_e32 v172, v172, v108
	v_sub_f32_e32 v175, v175, v108
	v_sub_f32_e32 v174, v174, v108
	v_pk_mul_f32 v[174:175], v[108:109], v[174:175] op_sel:[1,0]
	v_pk_mul_f32 v[172:173], v[108:109], v[172:173] op_sel:[1,0]
	v_pk_fma_f32 v[174:175], v[86:87], v[174:175], v[102:103]
	v_pk_fma_f32 v[172:173], v[84:85], v[172:173], v[100:101]
	v_pk_add_f32 v[36:37], v[36:37], v[174:175]
	v_pk_add_f32 v[34:35], v[34:35], v[172:173]
	global_store_dwordx4 v[130:131], v[34:37], off offset:192
	s_waitcnt vmcnt(15)
	v_sub_f32_e32 v177, v177, v110
	v_sub_f32_e32 v176, v176, v110
	v_sub_f32_e32 v179, v179, v110
	v_sub_f32_e32 v178, v178, v110
	v_pk_mul_f32 v[178:179], v[110:111], v[178:179] op_sel:[1,0]
	v_pk_mul_f32 v[176:177], v[110:111], v[176:177] op_sel:[1,0]
	v_pk_fma_f32 v[178:179], v[74:75], v[178:179], v[90:91]
	v_pk_fma_f32 v[176:177], v[72:73], v[176:177], v[88:89]
	v_pk_add_f32 v[32:33], v[32:33], v[178:179]
	v_pk_add_f32 v[30:31], v[30:31], v[176:177]
	global_store_dwordx4 v[134:135], v[30:33], off
	s_waitcnt vmcnt(15)
	v_sub_f32_e32 v181, v181, v110
	v_sub_f32_e32 v180, v180, v110
	v_sub_f32_e32 v183, v183, v110
	v_sub_f32_e32 v182, v182, v110
	v_pk_mul_f32 v[182:183], v[110:111], v[182:183] op_sel:[1,0]
	v_pk_mul_f32 v[180:181], v[110:111], v[180:181] op_sel:[1,0]
	v_pk_fma_f32 v[182:183], v[78:79], v[182:183], v[94:95]
	v_pk_fma_f32 v[180:181], v[76:77], v[180:181], v[92:93]
	v_pk_add_f32 v[28:29], v[28:29], v[182:183]
	v_pk_add_f32 v[26:27], v[26:27], v[180:181]
	global_store_dwordx4 v[134:135], v[26:29], off offset:64
	s_waitcnt vmcnt(15)
	v_sub_f32_e32 v185, v185, v110
	v_sub_f32_e32 v184, v184, v110
	v_sub_f32_e32 v187, v187, v110
	v_sub_f32_e32 v186, v186, v110
	v_pk_mul_f32 v[186:187], v[110:111], v[186:187] op_sel:[1,0]
	v_pk_mul_f32 v[184:185], v[110:111], v[184:185] op_sel:[1,0]
	v_pk_fma_f32 v[186:187], v[82:83], v[186:187], v[98:99]
	v_pk_fma_f32 v[184:185], v[80:81], v[184:185], v[96:97]
	v_pk_add_f32 v[24:25], v[24:25], v[186:187]
	v_pk_add_f32 v[22:23], v[22:23], v[184:185]
	global_store_dwordx4 v[134:135], v[22:25], off offset:128
	s_waitcnt vmcnt(15)
	v_sub_f32_e32 v189, v189, v110
	v_sub_f32_e32 v188, v188, v110
	v_sub_f32_e32 v191, v191, v110
	v_sub_f32_e32 v190, v190, v110
	v_pk_mul_f32 v[190:191], v[110:111], v[190:191] op_sel:[1,0]
	v_pk_mul_f32 v[188:189], v[110:111], v[188:189] op_sel:[1,0]
	v_pk_fma_f32 v[190:191], v[86:87], v[190:191], v[102:103]
	v_pk_fma_f32 v[188:189], v[84:85], v[188:189], v[100:101]
	v_pk_add_f32 v[20:21], v[20:21], v[190:191]
	v_pk_add_f32 v[18:19], v[18:19], v[188:189]
	global_store_dwordx4 v[134:135], v[18:21], off offset:192
	s_waitcnt vmcnt(15)
	v_sub_f32_e32 v193, v193, v140
	v_sub_f32_e32 v192, v192, v140
	v_sub_f32_e32 v195, v195, v140
	v_sub_f32_e32 v194, v194, v140
	v_pk_mul_f32 v[194:195], v[140:141], v[194:195] op_sel:[1,0]
	v_pk_mul_f32 v[192:193], v[140:141], v[192:193] op_sel:[1,0]
	v_pk_fma_f32 v[194:195], v[74:75], v[194:195], v[90:91]
	v_pk_fma_f32 v[192:193], v[72:73], v[192:193], v[88:89]
	v_pk_add_f32 v[16:17], v[16:17], v[194:195]
	v_pk_add_f32 v[14:15], v[14:15], v[192:193]
	global_store_dwordx4 v[138:139], v[14:17], off
	s_waitcnt vmcnt(15)
	v_sub_f32_e32 v197, v197, v140
	v_sub_f32_e32 v196, v196, v140
	v_sub_f32_e32 v199, v199, v140
	v_sub_f32_e32 v198, v198, v140
	v_pk_mul_f32 v[198:199], v[140:141], v[198:199] op_sel:[1,0]
	v_pk_mul_f32 v[196:197], v[140:141], v[196:197] op_sel:[1,0]
	v_pk_fma_f32 v[198:199], v[78:79], v[198:199], v[94:95]
	v_pk_fma_f32 v[196:197], v[76:77], v[196:197], v[92:93]
	v_pk_add_f32 v[8:9], v[8:9], v[198:199]
	v_pk_add_f32 v[6:7], v[6:7], v[196:197]
	global_store_dwordx4 v[138:139], v[6:9], off offset:64
	s_waitcnt vmcnt(15)
	v_sub_f32_e32 v201, v201, v140
	v_sub_f32_e32 v200, v200, v140
	v_sub_f32_e32 v203, v203, v140
	v_sub_f32_e32 v202, v202, v140
	v_pk_mul_f32 v[202:203], v[140:141], v[202:203] op_sel:[1,0]
	v_pk_mul_f32 v[200:201], v[140:141], v[200:201] op_sel:[1,0]
	v_pk_fma_f32 v[202:203], v[82:83], v[202:203], v[98:99]
	v_pk_fma_f32 v[200:201], v[80:81], v[200:201], v[96:97]
	v_pk_add_f32 v[12:13], v[12:13], v[202:203]
	v_pk_add_f32 v[10:11], v[10:11], v[200:201]
	global_store_dwordx4 v[138:139], v[10:13], off offset:128
	s_waitcnt vmcnt(15)
	v_sub_f32_e32 v217, v217, v140
	v_sub_f32_e32 v216, v216, v140
	v_sub_f32_e32 v219, v219, v140
	v_sub_f32_e32 v218, v218, v140
	v_pk_mul_f32 v[218:219], v[140:141], v[218:219] op_sel:[1,0]
	v_pk_mul_f32 v[216:217], v[140:141], v[216:217] op_sel:[1,0]
	v_pk_fma_f32 v[218:219], v[86:87], v[218:219], v[102:103]
	v_pk_fma_f32 v[216:217], v[84:85], v[216:217], v[100:101]
	v_pk_add_f32 v[4:5], v[4:5], v[218:219]
	v_pk_add_f32 v[2:3], v[2:3], v[216:217]
	global_store_dwordx4 v[138:139], v[2:5], off offset:192
	s_andn2_b64 vcc, exec, s[40:41]
	s_cbranch_vccz .LBB0_224

; DEVI unsigned pk_bf16(float lo, float hi) { const bf16x2n r = __builtin_convertvector((f32x2v){lo, hi}, bf16x2n); return __builtin_bit_cast(unsigned, r); }
; DEVI float sigmoidf_(float x) { return rcp_(1.0f + fast_exp2(-x * LOG2E)); }
; DEVI void phase_glu(const Params& p, int l, bf16_t* smem) {
;     ...
; #pragma unroll
;         for (int mi = 0; mi < 4; ++mi)
; #pragma unroll
;             for (int ni = 0; ni < 4; ++ni) {
;                 const int row = tm * 128 + wr * 64 + mi * 16 + l16, col = tn * 128 + wc * 64 + ni * 16 + quad * 4;
;                 const u32x2 yb = *(const u32x2*)(A + (size_t)row * 256 + col);
;                 const f32x4 gb4 = *(const f32x4*)(gb + col);
;                 float o[4];
;                 o[0] = __uint_as_float(yb.x << 16) * sigmoidf_(acc[mi][ni][0] + gb4[0]);
;                 o[1] = __uint_as_float(yb.x & 0xffff0000u) * sigmoidf_(acc[mi][ni][1] + gb4[1]);
;                 o[2] = __uint_as_float(yb.y << 16) * sigmoidf_(acc[mi][ni][2] + gb4[2]);
;                 o[3] = __uint_as_float(yb.y & 0xffff0000u) * sigmoidf_(acc[mi][ni][3] + gb4[3]);
;                 u32x2 pk; pk.x = pk_bf16(o[0], o[1]); pk.y = pk_bf16(o[2], o[3]);
;                 *(u32x2*)(cat + (size_t)row * 1024 + 768 + col) = pk;
;             }
.LBB0_227:
	v_lshl_or_b32 v74, s30, 7, v78
	v_ashrrev_i32_e32 v75, 31, v74
	v_lshl_add_u64 v[66:67], v[74:75], 2, s[14:15]
	s_barrier
	v_lshl_add_u32 v70, s26, 7, v0
	v_ashrrev_i32_e32 v71, 31, v70
	v_lshlrev_b64 v[72:73], 9, v[70:71]
	v_lshlrev_b64 v[68:69], 1, v[74:75]
	v_lshl_add_u64 v[72:73], s[0:1], 0, v[72:73]
	v_lshl_add_u64 v[76:77], v[72:73], 0, v[68:69]
	v_lshlrev_b64 v[72:73], 11, v[70:71]
	v_lshl_add_u64 v[72:73], s[8:9], 0, v[72:73]
	s_mov_b64 s[26:27], 0xe218600
	v_lshl_add_u64 v[72:73], v[72:73], 0, s[26:27]
	v_lshl_add_u64 v[86:87], v[72:73], 0, v[68:69]
	s_add_i32 s11, s11, 1
	s_mov_b64 s[40:41], 0
	global_load_dwordx4 v[88:91], v[66:67], off
	global_load_dwordx4 v[92:95], v[66:67], off offset:64
	global_load_dwordx4 v[96:99], v[66:67], off offset:128
	global_load_dwordx4 v[100:103], v[66:67], off offset:192
	v_lshl_add_u64 v[104:105], v[76:77], 0, s[36:37]
	v_lshl_add_u64 v[106:107], v[104:105], 0, s[36:37]
	v_lshl_add_u64 v[108:109], v[106:107], 0, s[36:37]
	s_mov_b64 s[26:27], 0x8000
	v_lshl_add_u64 v[110:111], v[86:87], 0, s[26:27]
	v_lshl_add_u64 v[112:113], v[110:111], 0, s[26:27]
	v_lshl_add_u64 v[114:115], v[112:113], 0, s[26:27]
	global_load_dwordx2 v[116:117], v[76:77], off
	global_load_dwordx2 v[118:119], v[76:77], off offset:32
	global_load_dwordx2 v[120:121], v[76:77], off offset:64
	global_load_dwordx2 v[122:123], v[76:77], off offset:96
	global_load_dwordx2 v[124:125], v[104:105], off
	global_load_dwordx2 v[126:127], v[104:105], off offset:32
	global_load_dwordx2 v[128:129], v[104:105], off offset:64
	global_load_dwordx2 v[130:131], v[104:105], off offset:96
	global_load_dwordx2 v[160:161], v[106:107], off
	global_load_dwordx2 v[162:163], v[106:107], off offset:32
	global_load_dwordx2 v[164:165], v[106:107], off offset:64
	global_load_dwordx2 v[166:167], v[106:107], off offset:96
	global_load_dwordx2 v[168:169], v[108:109], off
	global_load_dwordx2 v[170:171], v[108:109], off offset:32
	global_load_dwordx2 v[172:173], v[108:109], off offset:64
	global_load_dwordx2 v[174:175], v[108:109], off offset:96
	s_waitcnt vmcnt(15)
	v_add_f32_e32 v176, v62, v88
	v_add_f32_e32 v177, v63, v89
	v_add_f32_e32 v178, v64, v90
	v_add_f32_e32 v179, v65, v91
	v_mul_f32_e32 v176, 0xbfb8aa3b, v176
	v_mul_f32_e32 v177, 0xbfb8aa3b, v177
	v_mul_f32_e32 v178, 0xbfb8aa3b, v178
	v_mul_f32_e32 v179, 0xbfb8aa3b, v179
	v_exp_f32_e32 v176, v176
	v_exp_f32_e32 v177, v177
	v_exp_f32_e32 v178, v178
	v_exp_f32_e32 v179, v179
	v_add_f32_e32 v176, 1.0, v176
	v_add_f32_e32 v177, 1.0, v177
	v_add_f32_e32 v178, 1.0, v178
	v_add_f32_e32 v179, 1.0, v179
	v_rcp_f32_e32 v176, v176
	v_rcp_f32_e32 v177, v177
	v_rcp_f32_e32 v178, v178
	v_rcp_f32_e32 v179, v179
	v_lshlrev_b32_e32 v180, 16, v116
	v_and_b32_e32 v181, 0xffff0000, v116
	v_lshlrev_b32_e32 v182, 16, v117
	v_and_b32_e32 v183, 0xffff0000, v117
	v_pk_mul_f32 v[176:177], v[176:177], v[180:181]
	v_pk_mul_f32 v[178:179], v[178:179], v[182:183]
	v_cvt_pk_bf16_f32 v184, v176, v177
	v_cvt_pk_bf16_f32 v185, v178, v179
	global_store_dwordx2 v[86:87], v[184:185], off
	s_waitcnt vmcnt(15)
	v_add_f32_e32 v176, v58, v92
	v_add_f32_e32 v177, v59, v93
	v_add_f32_e32 v178, v60, v94
	v_add_f32_e32 v179, v61, v95
	v_mul_f32_e32 v176, 0xbfb8aa3b, v176
	v_mul_f32_e32 v177, 0xbfb8aa3b, v177
	v_mul_f32_e32 v178, 0xbfb8aa3b, v178
	v_mul_f32_e32 v179, 0xbfb8aa3b, v179
	v_exp_f32_e32 v176, v176
	v_exp_f32_e32 v177, v177
	v_exp_f32_e32 v178, v178
	v_exp_f32_e32 v179, v179
	v_add_f32_e32 v176, 1.0, v176
	v_add_f32_e32 v177, 1.0, v177
	v_add_f32_e32 v178, 1.0, v178
	v_add_f32_e32 v179, 1.0, v179
	v_rcp_f32_e32 v176, v176
	v_rcp_f32_e32 v177, v177
	v_rcp_f32_e32 v178, v178
	v_rcp_f32_e32 v179, v179
	v_lshlrev_b32_e32 v180, 16, v118
	v_and_b32_e32 v181, 0xffff0000, v118
	v_lshlrev_b32_e32 v182, 16, v119
	v_and_b32_e32 v183, 0xffff0000, v119
	v_pk_mul_f32 v[176:177], v[176:177], v[180:181]
	v_pk_mul_f32 v[178:179], v[178:179], v[182:183]
	v_cvt_pk_bf16_f32 v186, v176, v177
	v_cvt_pk_bf16_f32 v187, v178, v179
	global_store_dwordx2 v[86:87], v[186:187], off offset:32
	s_waitcnt vmcnt(15)
	v_add_f32_e32 v176, v54, v96
	v_add_f32_e32 v177, v55, v97
	v_add_f32_e32 v178, v56, v98
	v_add_f32_e32 v179, v57, v99
	v_mul_f32_e32 v176, 0xbfb8aa3b, v176
	v_mul_f32_e32 v177, 0xbfb8aa3b, v177
	v_mul_f32_e32 v178, 0xbfb8aa3b, v178
	v_mul_f32_e32 v179, 0xbfb8aa3b, v179
	v_exp_f32_e32 v176, v176
	v_exp_f32_e32 v177, v177
	v_exp_f32_e32 v178, v178
	v_exp_f32_e32 v179, v179
	v_add_f32_e32 v176, 1.0, v176
	v_add_f32_e32 v177, 1.0, v177
	v_add_f32_e32 v178, 1.0, v178
	v_add_f32_e32 v179, 1.0, v179
	v_rcp_f32_e32 v176, v176
	v_rcp_f32_e32 v177, v177
	v_rcp_f32_e32 v178, v178
	v_rcp_f32_e32 v179, v179
	v_lshlrev_b32_e32 v180, 16, v120
	v_and_b32_e32 v181, 0xffff0000, v120
	v_lshlrev_b32_e32 v182, 16, v121
	v_and_b32_e32 v183, 0xffff0000, v121
	v_pk_mul_f32 v[176:177], v[176:177], v[180:181]
	v_pk_mul_f32 v[178:179], v[178:179], v[182:183]
	v_cvt_pk_bf16_f32 v184, v176, v177
	v_cvt_pk_bf16_f32 v185, v178, v179
	global_store_dwordx2 v[86:87], v[184:185], off offset:64
	s_waitcnt vmcnt(15)
	v_add_f32_e32 v176, v50, v100
	v_add_f32_e32 v177, v51, v101
	v_add_f32_e32 v178, v52, v102
	v_add_f32_e32 v179, v53, v103
	v_mul_f32_e32 v176, 0xbfb8aa3b, v176
	v_mul_f32_e32 v177, 0xbfb8aa3b, v177
	v_mul_f32_e32 v178, 0xbfb8aa3b, v178
	v_mul_f32_e32 v179, 0xbfb8aa3b, v179
	v_exp_f32_e32 v176, v176
	v_exp_f32_e32 v177, v177
	v_exp_f32_e32 v178, v178
	v_exp_f32_e32 v179, v179
	v_add_f32_e32 v176, 1.0, v176
	v_add_f32_e32 v177, 1.0, v177
	v_add_f32_e32 v178, 1.0, v178
	v_add_f32_e32 v179, 1.0, v179
	v_rcp_f32_e32 v176, v176
	v_rcp_f32_e32 v177, v177
	v_rcp_f32_e32 v178, v178
	v_rcp_f32_e32 v179, v179
	v_lshlrev_b32_e32 v180, 16, v122
	v_and_b32_e32 v181, 0xffff0000, v122
	v_lshlrev_b32_e32 v182, 16, v123
	v_and_b32_e32 v183, 0xffff0000, v123
	v_pk_mul_f32 v[176:177], v[176:177], v[180:181]
	v_pk_mul_f32 v[178:179], v[178:179], v[182:183]
	v_cvt_pk_bf16_f32 v186, v176, v177
	v_cvt_pk_bf16_f32 v187, v178, v179
	global_store_dwordx2 v[86:87], v[186:187], off offset:96
	s_waitcnt vmcnt(15)
; DEVI unsigned pk_bf16(float lo, float hi) { const bf16x2n r = __builtin_convertvector((f32x2v){lo, hi}, bf16x2n); return __builtin_bit_cast(unsigned, r); }
; DEVI float sigmoidf_(float x) { return rcp_(1.0f + fast_exp2(-x * LOG2E)); }
; DEVI void phase_glu(const Params& p, int l, bf16_t* smem) {
;     ...
; #pragma unroll
;         for (int mi = 0; mi < 4; ++mi)
; #pragma unroll
;             for (int ni = 0; ni < 4; ++ni) {
;                 const int row = tm * 128 + wr * 64 + mi * 16 + l16, col = tn * 128 + wc * 64 + ni * 16 + quad * 4;
;                 const u32x2 yb = *(const u32x2*)(A + (size_t)row * 256 + col);
;                 const f32x4 gb4 = *(const f32x4*)(gb + col);
;                 float o[4];
;                 o[0] = __uint_as_float(yb.x << 16) * sigmoidf_(acc[mi][ni][0] + gb4[0]);
;                 o[1] = __uint_as_float(yb.x & 0xffff0000u) * sigmoidf_(acc[mi][ni][1] + gb4[1]);
;                 o[2] = __uint_as_float(yb.y << 16) * sigmoidf_(acc[mi][ni][2] + gb4[2]);
;                 o[3] = __uint_as_float(yb.y & 0xffff0000u) * sigmoidf_(acc[mi][ni][3] + gb4[3]);
;                 u32x2 pk; pk.x = pk_bf16(o[0], o[1]); pk.y = pk_bf16(o[2], o[3]);
;                 *(u32x2*)(cat + (size_t)row * 1024 + 768 + col) = pk;
;             }
	v_add_f32_e32 v176, v46, v88
	v_add_f32_e32 v177, v47, v89
	v_add_f32_e32 v178, v48, v90
	v_add_f32_e32 v179, v49, v91
	v_mul_f32_e32 v176, 0xbfb8aa3b, v176
	v_mul_f32_e32 v177, 0xbfb8aa3b, v177
	v_mul_f32_e32 v178, 0xbfb8aa3b, v178
	v_mul_f32_e32 v179, 0xbfb8aa3b, v179
	v_exp_f32_e32 v176, v176
	v_exp_f32_e32 v177, v177
	v_exp_f32_e32 v178, v178
	v_exp_f32_e32 v179, v179
	v_add_f32_e32 v176, 1.0, v176
	v_add_f32_e32 v177, 1.0, v177
	v_add_f32_e32 v178, 1.0, v178
	v_add_f32_e32 v179, 1.0, v179
	v_rcp_f32_e32 v176, v176
	v_rcp_f32_e32 v177, v177
	v_rcp_f32_e32 v178, v178
	v_rcp_f32_e32 v179, v179
	v_lshlrev_b32_e32 v180, 16, v124
	v_and_b32_e32 v181, 0xffff0000, v124
	v_lshlrev_b32_e32 v182, 16, v125
	v_and_b32_e32 v183, 0xffff0000, v125
	v_pk_mul_f32 v[176:177], v[176:177], v[180:181]
	v_pk_mul_f32 v[178:179], v[178:179], v[182:183]
	v_cvt_pk_bf16_f32 v184, v176, v177
	v_cvt_pk_bf16_f32 v185, v178, v179
	global_store_dwordx2 v[110:111], v[184:185], off
	s_waitcnt vmcnt(15)
	v_add_f32_e32 v176, v42, v92
	v_add_f32_e32 v177, v43, v93
	v_add_f32_e32 v178, v44, v94
	v_add_f32_e32 v179, v45, v95
	v_mul_f32_e32 v176, 0xbfb8aa3b, v176
	v_mul_f32_e32 v177, 0xbfb8aa3b, v177
	v_mul_f32_e32 v178, 0xbfb8aa3b, v178
	v_mul_f32_e32 v179, 0xbfb8aa3b, v179
	v_exp_f32_e32 v176, v176
	v_exp_f32_e32 v177, v177
	v_exp_f32_e32 v178, v178
	v_exp_f32_e32 v179, v179
	v_add_f32_e32 v176, 1.0, v176
	v_add_f32_e32 v177, 1.0, v177
	v_add_f32_e32 v178, 1.0, v178
	v_add_f32_e32 v179, 1.0, v179
	v_rcp_f32_e32 v176, v176
	v_rcp_f32_e32 v177, v177
	v_rcp_f32_e32 v178, v178
	v_rcp_f32_e32 v179, v179
	v_lshlrev_b32_e32 v180, 16, v126
	v_and_b32_e32 v181, 0xffff0000, v126
	v_lshlrev_b32_e32 v182, 16, v127
	v_and_b32_e32 v183, 0xffff0000, v127
	v_pk_mul_f32 v[176:177], v[176:177], v[180:181]
	v_pk_mul_f32 v[178:179], v[178:179], v[182:183]
	v_cvt_pk_bf16_f32 v186, v176, v177
	v_cvt_pk_bf16_f32 v187, v178, v179
	global_store_dwordx2 v[110:111], v[186:187], off offset:32
	s_waitcnt vmcnt(15)
	v_add_f32_e32 v176, v38, v96
	v_add_f32_e32 v177, v39, v97
	v_add_f32_e32 v178, v40, v98
	v_add_f32_e32 v179, v41, v99
	v_mul_f32_e32 v176, 0xbfb8aa3b, v176
	v_mul_f32_e32 v177, 0xbfb8aa3b, v177
	v_mul_f32_e32 v178, 0xbfb8aa3b, v178
	v_mul_f32_e32 v179, 0xbfb8aa3b, v179
	v_exp_f32_e32 v176, v176
	v_exp_f32_e32 v177, v177
	v_exp_f32_e32 v178, v178
	v_exp_f32_e32 v179, v179
	v_add_f32_e32 v176, 1.0, v176
	v_add_f32_e32 v177, 1.0, v177
	v_add_f32_e32 v178, 1.0, v178
	v_add_f32_e32 v179, 1.0, v179
	v_rcp_f32_e32 v176, v176
	v_rcp_f32_e32 v177, v177
	v_rcp_f32_e32 v178, v178
	v_rcp_f32_e32 v179, v179
	v_lshlrev_b32_e32 v180, 16, v128
	v_and_b32_e32 v181, 0xffff0000, v128
	v_lshlrev_b32_e32 v182, 16, v129
	v_and_b32_e32 v183, 0xffff0000, v129
	v_pk_mul_f32 v[176:177], v[176:177], v[180:181]
	v_pk_mul_f32 v[178:179], v[178:179], v[182:183]
	v_cvt_pk_bf16_f32 v184, v176, v177
	v_cvt_pk_bf16_f32 v185, v178, v179
	global_store_dwordx2 v[110:111], v[184:185], off offset:64
	s_waitcnt vmcnt(15)
	v_add_f32_e32 v176, v34, v100
	v_add_f32_e32 v177, v35, v101
	v_add_f32_e32 v178, v36, v102
	v_add_f32_e32 v179, v37, v103
	v_mul_f32_e32 v176, 0xbfb8aa3b, v176
	v_mul_f32_e32 v177, 0xbfb8aa3b, v177
	v_mul_f32_e32 v178, 0xbfb8aa3b, v178
	v_mul_f32_e32 v179, 0xbfb8aa3b, v179
	v_exp_f32_e32 v176, v176
	v_exp_f32_e32 v177, v177
	v_exp_f32_e32 v178, v178
	v_exp_f32_e32 v179, v179
	v_add_f32_e32 v176, 1.0, v176
	v_add_f32_e32 v177, 1.0, v177
	v_add_f32_e32 v178, 1.0, v178
	v_add_f32_e32 v179, 1.0, v179
	v_rcp_f32_e32 v176, v176
	v_rcp_f32_e32 v177, v177
	v_rcp_f32_e32 v178, v178
	v_rcp_f32_e32 v179, v179
	v_lshlrev_b32_e32 v180, 16, v130
	v_and_b32_e32 v181, 0xffff0000, v130
	v_lshlrev_b32_e32 v182, 16, v131
	v_and_b32_e32 v183, 0xffff0000, v131
	v_pk_mul_f32 v[176:177], v[176:177], v[180:181]
	v_pk_mul_f32 v[178:179], v[178:179], v[182:183]
	v_cvt_pk_bf16_f32 v186, v176, v177
	v_cvt_pk_bf16_f32 v187, v178, v179
	global_store_dwordx2 v[110:111], v[186:187], off offset:96
	s_waitcnt vmcnt(15)
	v_add_f32_e32 v176, v30, v88
	v_add_f32_e32 v177, v31, v89
	v_add_f32_e32 v178, v32, v90
	v_add_f32_e32 v179, v33, v91
	v_mul_f32_e32 v176, 0xbfb8aa3b, v176
	v_mul_f32_e32 v177, 0xbfb8aa3b, v177
	v_mul_f32_e32 v178, 0xbfb8aa3b, v178
	v_mul_f32_e32 v179, 0xbfb8aa3b, v179
	v_exp_f32_e32 v176, v176
	v_exp_f32_e32 v177, v177
	v_exp_f32_e32 v178, v178
	v_exp_f32_e32 v179, v179
	v_add_f32_e32 v176, 1.0, v176
	v_add_f32_e32 v177, 1.0, v177
	v_add_f32_e32 v178, 1.0, v178
	v_add_f32_e32 v179, 1.0, v179
	v_rcp_f32_e32 v176, v176
	v_rcp_f32_e32 v177, v177
	v_rcp_f32_e32 v178, v178
	v_rcp_f32_e32 v179, v179
	v_lshlrev_b32_e32 v180, 16, v160
	v_and_b32_e32 v181, 0xffff0000, v160
	v_lshlrev_b32_e32 v182, 16, v161
	v_and_b32_e32 v183, 0xffff0000, v161
	v_pk_mul_f32 v[176:177], v[176:177], v[180:181]
	v_pk_mul_f32 v[178:179], v[178:179], v[182:183]
	v_cvt_pk_bf16_f32 v184, v176, v177
	v_cvt_pk_bf16_f32 v185, v178, v179
	global_store_dwordx2 v[112:113], v[184:185], off
	s_waitcnt vmcnt(15)
	v_add_f32_e32 v176, v26, v92
	v_add_f32_e32 v177, v27, v93
	v_add_f32_e32 v178, v28, v94
	v_add_f32_e32 v179, v29, v95
	v_mul_f32_e32 v176, 0xbfb8aa3b, v176
	v_mul_f32_e32 v177, 0xbfb8aa3b, v177
	v_mul_f32_e32 v178, 0xbfb8aa3b, v178
	v_mul_f32_e32 v179, 0xbfb8aa3b, v179
	v_exp_f32_e32 v176, v176
	v_exp_f32_e32 v177, v177
	v_exp_f32_e32 v178, v178
	v_exp_f32_e32 v179, v179
	v_add_f32_e32 v176, 1.0, v176
	v_add_f32_e32 v177, 1.0, v177
	v_add_f32_e32 v178, 1.0, v178
	v_add_f32_e32 v179, 1.0, v179
	v_rcp_f32_e32 v176, v176
	v_rcp_f32_e32 v177, v177
	v_rcp_f32_e32 v178, v178
	v_rcp_f32_e32 v179, v179
	v_lshlrev_b32_e32 v180, 16, v162
	v_and_b32_e32 v181, 0xffff0000, v162
	v_lshlrev_b32_e32 v182, 16, v163
	v_and_b32_e32 v183, 0xffff0000, v163
	v_pk_mul_f32 v[176:177], v[176:177], v[180:181]
	v_pk_mul_f32 v[178:179], v[178:179], v[182:183]
	v_cvt_pk_bf16_f32 v186, v176, v177
	v_cvt_pk_bf16_f32 v187, v178, v179
	global_store_dwordx2 v[112:113], v[186:187], off offset:32
	s_waitcnt vmcnt(15)
; DEVI unsigned pk_bf16(float lo, float hi) { const bf16x2n r = __builtin_convertvector((f32x2v){lo, hi}, bf16x2n); return __builtin_bit_cast(unsigned, r); }
; DEVI float sigmoidf_(float x) { return rcp_(1.0f + fast_exp2(-x * LOG2E)); }
; DEVI void phase_glu(const Params& p, int l, bf16_t* smem) {
;     ...
; #pragma unroll
;         for (int mi = 0; mi < 4; ++mi)
; #pragma unroll
;             for (int ni = 0; ni < 4; ++ni) {
;                 const int row = tm * 128 + wr * 64 + mi * 16 + l16, col = tn * 128 + wc * 64 + ni * 16 + quad * 4;
;                 const u32x2 yb = *(const u32x2*)(A + (size_t)row * 256 + col);
;                 const f32x4 gb4 = *(const f32x4*)(gb + col);
;                 float o[4];
;                 o[0] = __uint_as_float(yb.x << 16) * sigmoidf_(acc[mi][ni][0] + gb4[0]);
;                 o[1] = __uint_as_float(yb.x & 0xffff0000u) * sigmoidf_(acc[mi][ni][1] + gb4[1]);
;                 o[2] = __uint_as_float(yb.y << 16) * sigmoidf_(acc[mi][ni][2] + gb4[2]);
;                 o[3] = __uint_as_float(yb.y & 0xffff0000u) * sigmoidf_(acc[mi][ni][3] + gb4[3]);
;                 u32x2 pk; pk.x = pk_bf16(o[0], o[1]); pk.y = pk_bf16(o[2], o[3]);
;                 *(u32x2*)(cat + (size_t)row * 1024 + 768 + col) = pk;
;             }
	v_add_f32_e32 v176, v22, v96
	v_add_f32_e32 v177, v23, v97
	v_add_f32_e32 v178, v24, v98
	v_add_f32_e32 v179, v25, v99
	v_mul_f32_e32 v176, 0xbfb8aa3b, v176
	v_mul_f32_e32 v177, 0xbfb8aa3b, v177
	v_mul_f32_e32 v178, 0xbfb8aa3b, v178
	v_mul_f32_e32 v179, 0xbfb8aa3b, v179
	v_exp_f32_e32 v176, v176
	v_exp_f32_e32 v177, v177
	v_exp_f32_e32 v178, v178
	v_exp_f32_e32 v179, v179
	v_add_f32_e32 v176, 1.0, v176
	v_add_f32_e32 v177, 1.0, v177
	v_add_f32_e32 v178, 1.0, v178
	v_add_f32_e32 v179, 1.0, v179
	v_rcp_f32_e32 v176, v176
	v_rcp_f32_e32 v177, v177
	v_rcp_f32_e32 v178, v178
	v_rcp_f32_e32 v179, v179
	v_lshlrev_b32_e32 v180, 16, v164
	v_and_b32_e32 v181, 0xffff0000, v164
	v_lshlrev_b32_e32 v182, 16, v165
	v_and_b32_e32 v183, 0xffff0000, v165
	v_pk_mul_f32 v[176:177], v[176:177], v[180:181]
	v_pk_mul_f32 v[178:179], v[178:179], v[182:183]
	v_cvt_pk_bf16_f32 v184, v176, v177
	v_cvt_pk_bf16_f32 v185, v178, v179
	global_store_dwordx2 v[112:113], v[184:185], off offset:64
	s_waitcnt vmcnt(15)
	v_add_f32_e32 v176, v18, v100
	v_add_f32_e32 v177, v19, v101
	v_add_f32_e32 v178, v20, v102
	v_add_f32_e32 v179, v21, v103
	v_mul_f32_e32 v176, 0xbfb8aa3b, v176
	v_mul_f32_e32 v177, 0xbfb8aa3b, v177
	v_mul_f32_e32 v178, 0xbfb8aa3b, v178
	v_mul_f32_e32 v179, 0xbfb8aa3b, v179
	v_exp_f32_e32 v176, v176
	v_exp_f32_e32 v177, v177
	v_exp_f32_e32 v178, v178
	v_exp_f32_e32 v179, v179
	v_add_f32_e32 v176, 1.0, v176
	v_add_f32_e32 v177, 1.0, v177
	v_add_f32_e32 v178, 1.0, v178
	v_add_f32_e32 v179, 1.0, v179
	v_rcp_f32_e32 v176, v176
	v_rcp_f32_e32 v177, v177
	v_rcp_f32_e32 v178, v178
	v_rcp_f32_e32 v179, v179
	v_lshlrev_b32_e32 v180, 16, v166
	v_and_b32_e32 v181, 0xffff0000, v166
	v_lshlrev_b32_e32 v182, 16, v167
	v_and_b32_e32 v183, 0xffff0000, v167
	v_pk_mul_f32 v[176:177], v[176:177], v[180:181]
	v_pk_mul_f32 v[178:179], v[178:179], v[182:183]
	v_cvt_pk_bf16_f32 v186, v176, v177
	v_cvt_pk_bf16_f32 v187, v178, v179
	global_store_dwordx2 v[112:113], v[186:187], off offset:96
	s_waitcnt vmcnt(15)
	v_add_f32_e32 v176, v14, v88
	v_add_f32_e32 v177, v15, v89
	v_add_f32_e32 v178, v16, v90
	v_add_f32_e32 v179, v17, v91
	v_mul_f32_e32 v176, 0xbfb8aa3b, v176
	v_mul_f32_e32 v177, 0xbfb8aa3b, v177
	v_mul_f32_e32 v178, 0xbfb8aa3b, v178
	v_mul_f32_e32 v179, 0xbfb8aa3b, v179
	v_exp_f32_e32 v176, v176
	v_exp_f32_e32 v177, v177
	v_exp_f32_e32 v178, v178
	v_exp_f32_e32 v179, v179
	v_add_f32_e32 v176, 1.0, v176
	v_add_f32_e32 v177, 1.0, v177
	v_add_f32_e32 v178, 1.0, v178
	v_add_f32_e32 v179, 1.0, v179
	v_rcp_f32_e32 v176, v176
	v_rcp_f32_e32 v177, v177
	v_rcp_f32_e32 v178, v178
	v_rcp_f32_e32 v179, v179
	v_lshlrev_b32_e32 v180, 16, v168
	v_and_b32_e32 v181, 0xffff0000, v168
	v_lshlrev_b32_e32 v182, 16, v169
	v_and_b32_e32 v183, 0xffff0000, v169
	v_pk_mul_f32 v[176:177], v[176:177], v[180:181]
	v_pk_mul_f32 v[178:179], v[178:179], v[182:183]
	v_cvt_pk_bf16_f32 v184, v176, v177
	v_cvt_pk_bf16_f32 v185, v178, v179
	global_store_dwordx2 v[114:115], v[184:185], off
	s_waitcnt vmcnt(15)
	v_add_f32_e32 v176, v10, v92
	v_add_f32_e32 v177, v11, v93
	v_add_f32_e32 v178, v12, v94
	v_add_f32_e32 v179, v13, v95
	v_mul_f32_e32 v176, 0xbfb8aa3b, v176
	v_mul_f32_e32 v177, 0xbfb8aa3b, v177
	v_mul_f32_e32 v178, 0xbfb8aa3b, v178
	v_mul_f32_e32 v179, 0xbfb8aa3b, v179
	v_exp_f32_e32 v176, v176
	v_exp_f32_e32 v177, v177
	v_exp_f32_e32 v178, v178
	v_exp_f32_e32 v179, v179
	v_add_f32_e32 v176, 1.0, v176
	v_add_f32_e32 v177, 1.0, v177
	v_add_f32_e32 v178, 1.0, v178
	v_add_f32_e32 v179, 1.0, v179
	v_rcp_f32_e32 v176, v176
	v_rcp_f32_e32 v177, v177
	v_rcp_f32_e32 v178, v178
	v_rcp_f32_e32 v179, v179
	v_lshlrev_b32_e32 v180, 16, v170
	v_and_b32_e32 v181, 0xffff0000, v170
	v_lshlrev_b32_e32 v182, 16, v171
	v_and_b32_e32 v183, 0xffff0000, v171
	v_pk_mul_f32 v[176:177], v[176:177], v[180:181]
	v_pk_mul_f32 v[178:179], v[178:179], v[182:183]
	v_cvt_pk_bf16_f32 v186, v176, v177
	v_cvt_pk_bf16_f32 v187, v178, v179
	global_store_dwordx2 v[114:115], v[186:187], off offset:32
	s_waitcnt vmcnt(15)
	v_add_f32_e32 v176, v6, v96
	v_add_f32_e32 v177, v7, v97
	v_add_f32_e32 v178, v8, v98
	v_add_f32_e32 v179, v9, v99
	v_mul_f32_e32 v176, 0xbfb8aa3b, v176
	v_mul_f32_e32 v177, 0xbfb8aa3b, v177
	v_mul_f32_e32 v178, 0xbfb8aa3b, v178
	v_mul_f32_e32 v179, 0xbfb8aa3b, v179
	v_exp_f32_e32 v176, v176
	v_exp_f32_e32 v177, v177
	v_exp_f32_e32 v178, v178
	v_exp_f32_e32 v179, v179
	v_add_f32_e32 v176, 1.0, v176
	v_add_f32_e32 v177, 1.0, v177
	v_add_f32_e32 v178, 1.0, v178
	v_add_f32_e32 v179, 1.0, v179
	v_rcp_f32_e32 v176, v176
	v_rcp_f32_e32 v177, v177
	v_rcp_f32_e32 v178, v178
	v_rcp_f32_e32 v179, v179
	v_lshlrev_b32_e32 v180, 16, v172
	v_and_b32_e32 v181, 0xffff0000, v172
	v_lshlrev_b32_e32 v182, 16, v173
	v_and_b32_e32 v183, 0xffff0000, v173
	v_pk_mul_f32 v[176:177], v[176:177], v[180:181]
	v_pk_mul_f32 v[178:179], v[178:179], v[182:183]
	v_cvt_pk_bf16_f32 v184, v176, v177
	v_cvt_pk_bf16_f32 v185, v178, v179
	global_store_dwordx2 v[114:115], v[184:185], off offset:64
	s_waitcnt vmcnt(15)
	v_add_f32_e32 v176, v2, v100
	v_add_f32_e32 v177, v3, v101
	v_add_f32_e32 v178, v4, v102
	v_add_f32_e32 v179, v5, v103
	v_mul_f32_e32 v176, 0xbfb8aa3b, v176
	v_mul_f32_e32 v177, 0xbfb8aa3b, v177
	v_mul_f32_e32 v178, 0xbfb8aa3b, v178
	v_mul_f32_e32 v179, 0xbfb8aa3b, v179
	v_exp_f32_e32 v176, v176
	v_exp_f32_e32 v177, v177
	v_exp_f32_e32 v178, v178
	v_exp_f32_e32 v179, v179
	v_add_f32_e32 v176, 1.0, v176
	v_add_f32_e32 v177, 1.0, v177
	v_add_f32_e32 v178, 1.0, v178
	v_add_f32_e32 v179, 1.0, v179
	v_rcp_f32_e32 v176, v176
	v_rcp_f32_e32 v177, v177
	v_rcp_f32_e32 v178, v178
	v_rcp_f32_e32 v179, v179
	v_lshlrev_b32_e32 v180, 16, v174
	v_and_b32_e32 v181, 0xffff0000, v174
	v_lshlrev_b32_e32 v182, 16, v175
	v_and_b32_e32 v183, 0xffff0000, v175
	v_pk_mul_f32 v[176:177], v[176:177], v[180:181]
	v_pk_mul_f32 v[178:179], v[178:179], v[182:183]
	v_cvt_pk_bf16_f32 v186, v176, v177
	v_cvt_pk_bf16_f32 v187, v178, v179
	global_store_dwordx2 v[114:115], v[186:187], off offset:96

; DEVI void s5_pass_b(const Params& p, int l, int witem, unsigned char* wlraw) {
;     ...
;     {
;         const float2* E = (const float2*)(ws + OFF_E) + ((size_t)(b * 128) * 16 + G) * 64 + lane;
; #pragma unroll 8
;         for (int kk = 0; kk < k; ++kk) {
;             const float2 e = E[(size_t)kk * 16 * 64];
;             const float nr = a4.z * hr - a4.w * hi + e.x, ni = a4.z * hi + a4.w * hr + e.y;
;             hr = nr; hi = ni;
;         }
;     }
.LBB0_709:
	v_add_co_u32_e32 v82, vcc, 0xffff2000, v74
	s_nop 1
	v_addc_co_u32_e32 v83, vcc, -1, v75, vcc
	global_load_dwordx2 v[92:93], v[82:83], off
	v_add_co_u32_e32 v82, vcc, 0xffff4000, v74
	s_nop 1
	v_addc_co_u32_e32 v83, vcc, -1, v75, vcc
	global_load_dwordx2 v[94:95], v[82:83], off
	v_add_co_u32_e32 v82, vcc, 0xffff6000, v74
	s_nop 1
	v_addc_co_u32_e32 v83, vcc, -1, v75, vcc
	global_load_dwordx2 v[96:97], v[82:83], off
	v_add_co_u32_e32 v82, vcc, 0xffff8000, v74
	s_nop 1
	v_addc_co_u32_e32 v83, vcc, -1, v75, vcc
	global_load_dwordx2 v[98:99], v[82:83], off
	v_add_co_u32_e32 v82, vcc, 0xffffa000, v74
	s_nop 1
	v_addc_co_u32_e32 v83, vcc, -1, v75, vcc
	global_load_dwordx2 v[100:101], v[82:83], off
	v_add_co_u32_e32 v82, vcc, 0xffffc000, v74
	s_nop 1
	v_addc_co_u32_e32 v83, vcc, -1, v75, vcc
	global_load_dwordx2 v[102:103], v[82:83], off
	v_add_co_u32_e32 v82, vcc, 0xffffe000, v74
	s_nop 1
	v_addc_co_u32_e32 v83, vcc, -1, v75, vcc
	global_load_dwordx2 v[104:105], v[82:83], off
	global_load_dwordx2 v[106:107], v[74:75], off
	s_mov_b64 s[46:47], 0x10000
	v_lshl_add_u64 v[74:75], v[74:75], 0, s[46:47]
	v_mov_b32_e32 v80, v73
	v_pk_mul_f32 v[80:81], v[6:7], v[80:81] op_sel_hi:[1,0]
	s_nop 0
	v_pk_fma_f32 v[84:85], v[4:5], v[72:73], v[80:81] neg_lo:[0,0,1] neg_hi:[0,0,1]
	v_pk_fma_f32 v[72:73], v[4:5], v[72:73], v[80:81] op_sel_hi:[1,0,1]
	s_nop 0
	v_mov_b32_e32 v85, v73
	s_waitcnt vmcnt(7)
	v_pk_add_f32 v[72:73], v[84:85], v[92:93]
	s_nop 0
	v_pk_mul_f32 v[80:81], v[6:7], v[72:73] op_sel:[0,1]
	s_nop 0
	v_pk_fma_f32 v[84:85], v[4:5], v[72:73], v[80:81] neg_lo:[0,0,1] neg_hi:[0,0,1]
	v_pk_fma_f32 v[72:73], v[4:5], v[72:73], v[80:81] op_sel_hi:[1,0,1]
	s_nop 0
	v_mov_b32_e32 v85, v73
	s_waitcnt vmcnt(6)
	v_pk_add_f32 v[72:73], v[84:85], v[94:95]
	s_nop 0
	v_pk_mul_f32 v[80:81], v[6:7], v[72:73] op_sel:[0,1]
	s_nop 0
	v_pk_fma_f32 v[84:85], v[4:5], v[72:73], v[80:81] neg_lo:[0,0,1] neg_hi:[0,0,1]
	v_pk_fma_f32 v[72:73], v[4:5], v[72:73], v[80:81] op_sel_hi:[1,0,1]
	s_nop 0
	v_mov_b32_e32 v85, v73
	s_waitcnt vmcnt(5)
	v_pk_add_f32 v[72:73], v[84:85], v[96:97]
	s_nop 0
	v_pk_mul_f32 v[80:81], v[6:7], v[72:73] op_sel:[0,1]
	s_nop 0
	v_pk_fma_f32 v[84:85], v[4:5], v[72:73], v[80:81] neg_lo:[0,0,1] neg_hi:[0,0,1]
	v_pk_fma_f32 v[72:73], v[4:5], v[72:73], v[80:81] op_sel_hi:[1,0,1]
	s_nop 0
	v_mov_b32_e32 v85, v73
	s_waitcnt vmcnt(4)
	v_pk_add_f32 v[72:73], v[84:85], v[98:99]
	s_nop 0
	v_pk_mul_f32 v[80:81], v[6:7], v[72:73] op_sel:[0,1]
	s_nop 0
	v_pk_fma_f32 v[84:85], v[4:5], v[72:73], v[80:81] neg_lo:[0,0,1] neg_hi:[0,0,1]
	v_pk_fma_f32 v[72:73], v[4:5], v[72:73], v[80:81] op_sel_hi:[1,0,1]
	s_nop 0
	v_mov_b32_e32 v85, v73
	s_waitcnt vmcnt(3)
	v_pk_add_f32 v[72:73], v[84:85], v[100:101]
	s_nop 0
	v_pk_mul_f32 v[80:81], v[6:7], v[72:73] op_sel:[0,1]
	s_nop 0
	v_pk_fma_f32 v[84:85], v[4:5], v[72:73], v[80:81] neg_lo:[0,0,1] neg_hi:[0,0,1]
	v_pk_fma_f32 v[72:73], v[4:5], v[72:73], v[80:81] op_sel_hi:[1,0,1]
	s_nop 0
	v_mov_b32_e32 v85, v73
	s_waitcnt vmcnt(2)
	v_pk_add_f32 v[72:73], v[84:85], v[102:103]
	s_nop 0
	v_pk_mul_f32 v[80:81], v[6:7], v[72:73] op_sel:[0,1]
	s_nop 0
	v_pk_fma_f32 v[84:85], v[4:5], v[72:73], v[80:81] neg_lo:[0,0,1] neg_hi:[0,0,1]
	v_pk_fma_f32 v[72:73], v[4:5], v[72:73], v[80:81] op_sel_hi:[1,0,1]
	s_nop 0
	v_mov_b32_e32 v85, v73
	s_waitcnt vmcnt(1)
	v_pk_add_f32 v[72:73], v[84:85], v[104:105]
	s_nop 0
	v_pk_mul_f32 v[80:81], v[6:7], v[72:73] op_sel:[0,1]
	s_nop 0
	v_pk_fma_f32 v[84:85], v[4:5], v[72:73], v[80:81] neg_lo:[0,0,1] neg_hi:[0,0,1]
	v_pk_fma_f32 v[72:73], v[4:5], v[72:73], v[80:81] op_sel_hi:[1,0,1]
	s_nop 0
	v_mov_b32_e32 v85, v73
	s_waitcnt vmcnt(0)
	v_pk_add_f32 v[72:73], v[84:85], v[106:107]
	s_add_i32 s43, s43, 8
	s_cmp_eq_u32 s22, s43
	s_cbranch_scc0 .LBB0_709
	s_bfe_u32 s42, s42, 0x30004
	s_cmp_eq_u32 s42, 0
	s_cbranch_scc0 .LBB0_713
	s_branch .LBB0_715

; DEVI void s5_pass_b(const Params& p, int l, int witem, unsigned char* wlraw) {
;     ...
;     {
;         const float2* E = (const float2*)(ws + OFF_E) + ((size_t)(b * 128) * 16 + G) * 64 + lane;
; #pragma unroll 8
;         for (int kk = 0; kk < k; ++kk) {
;             const float2 e = E[(size_t)kk * 16 * 64];
;             const float nr = a4.z * hr - a4.w * hi + e.x, ni = a4.z * hi + a4.w * hr + e.y;
;             hr = nr; hi = ni;
;         }
;     }
.LBB0_714:
	global_load_dwordx2 v[92:93], v[74:75], off
	v_lshl_add_u64 v[82:83], v[74:75], 0, s[36:37]
	global_load_dwordx2 v[94:95], v[82:83], off
	v_lshl_add_u64 v[82:83], v[82:83], 0, s[36:37]
	global_load_dwordx2 v[96:97], v[82:83], off
	v_lshl_add_u64 v[82:83], v[82:83], 0, s[36:37]
	global_load_dwordx2 v[98:99], v[82:83], off
	v_lshl_add_u64 v[82:83], v[82:83], 0, s[36:37]
	global_load_dwordx2 v[100:101], v[82:83], off
	v_lshl_add_u64 v[82:83], v[82:83], 0, s[36:37]
	global_load_dwordx2 v[102:103], v[82:83], off
	v_lshl_add_u64 v[82:83], v[82:83], 0, s[36:37]
	global_load_dwordx2 v[104:105], v[82:83], off
	v_pk_mul_f32 v[82:83], v[6:7], v[0:1] op_sel_hi:[1,0]
	s_nop 0
	v_pk_fma_f32 v[84:85], v[4:5], v[72:73], v[82:83] neg_lo:[0,0,1] neg_hi:[0,0,1]
	v_pk_fma_f32 v[72:73], v[4:5], v[72:73], v[82:83] op_sel_hi:[1,0,1]
	s_nop 0
	v_mov_b32_e32 v85, v73
	s_waitcnt vmcnt(6)
	v_pk_add_f32 v[72:73], v[84:85], v[92:93]
	s_nop 0
	v_mov_b32_e32 v0, v73
	s_add_i32 s42, s42, -1
	s_cmp_lg_u32 s42, 0
	s_cbranch_scc0 .Ls5_tail_done
	v_pk_mul_f32 v[82:83], v[6:7], v[0:1] op_sel_hi:[1,0]
	s_nop 0
	v_pk_fma_f32 v[84:85], v[4:5], v[72:73], v[82:83] neg_lo:[0,0,1] neg_hi:[0,0,1]
	v_pk_fma_f32 v[72:73], v[4:5], v[72:73], v[82:83] op_sel_hi:[1,0,1]
	s_nop 0
	v_mov_b32_e32 v85, v73
	s_waitcnt vmcnt(5)
	v_pk_add_f32 v[72:73], v[84:85], v[94:95]
	s_nop 0
	v_mov_b32_e32 v0, v73
	s_add_i32 s42, s42, -1
	s_cmp_lg_u32 s42, 0
	s_cbranch_scc0 .Ls5_tail_done
	v_pk_mul_f32 v[82:83], v[6:7], v[0:1] op_sel_hi:[1,0]
	s_nop 0
	v_pk_fma_f32 v[84:85], v[4:5], v[72:73], v[82:83] neg_lo:[0,0,1] neg_hi:[0,0,1]
	v_pk_fma_f32 v[72:73], v[4:5], v[72:73], v[82:83] op_sel_hi:[1,0,1]
	s_nop 0
	v_mov_b32_e32 v85, v73
	s_waitcnt vmcnt(4)
	v_pk_add_f32 v[72:73], v[84:85], v[96:97]
	s_nop 0
	v_mov_b32_e32 v0, v73
	s_add_i32 s42, s42, -1
	s_cmp_lg_u32 s42, 0
	s_cbranch_scc0 .Ls5_tail_done
	v_pk_mul_f32 v[82:83], v[6:7], v[0:1] op_sel_hi:[1,0]
	s_nop 0
	v_pk_fma_f32 v[84:85], v[4:5], v[72:73], v[82:83] neg_lo:[0,0,1] neg_hi:[0,0,1]
	v_pk_fma_f32 v[72:73], v[4:5], v[72:73], v[82:83] op_sel_hi:[1,0,1]
	s_nop 0
	v_mov_b32_e32 v85, v73
	s_waitcnt vmcnt(3)
	v_pk_add_f32 v[72:73], v[84:85], v[98:99]
	s_nop 0
	v_mov_b32_e32 v0, v73
	s_add_i32 s42, s42, -1
	s_cmp_lg_u32 s42, 0
	s_cbranch_scc0 .Ls5_tail_done
	v_pk_mul_f32 v[82:83], v[6:7], v[0:1] op_sel_hi:[1,0]
	s_nop 0
	v_pk_fma_f32 v[84:85], v[4:5], v[72:73], v[82:83] neg_lo:[0,0,1] neg_hi:[0,0,1]
	v_pk_fma_f32 v[72:73], v[4:5], v[72:73], v[82:83] op_sel_hi:[1,0,1]
	s_nop 0
	v_mov_b32_e32 v85, v73
	s_waitcnt vmcnt(2)
	v_pk_add_f32 v[72:73], v[84:85], v[100:101]
	s_nop 0
	v_mov_b32_e32 v0, v73
	s_add_i32 s42, s42, -1
	s_cmp_lg_u32 s42, 0
	s_cbranch_scc0 .Ls5_tail_done
	v_pk_mul_f32 v[82:83], v[6:7], v[0:1] op_sel_hi:[1,0]
	s_nop 0
	v_pk_fma_f32 v[84:85], v[4:5], v[72:73], v[82:83] neg_lo:[0,0,1] neg_hi:[0,0,1]
	v_pk_fma_f32 v[72:73], v[4:5], v[72:73], v[82:83] op_sel_hi:[1,0,1]
	s_nop 0
	v_mov_b32_e32 v85, v73
	s_waitcnt vmcnt(1)
	v_pk_add_f32 v[72:73], v[84:85], v[102:103]
	s_nop 0
	v_mov_b32_e32 v0, v73
	s_add_i32 s42, s42, -1
	s_cmp_lg_u32 s42, 0
	s_cbranch_scc0 .Ls5_tail_done
	v_pk_mul_f32 v[82:83], v[6:7], v[0:1] op_sel_hi:[1,0]
	s_nop 0
	v_pk_fma_f32 v[84:85], v[4:5], v[72:73], v[82:83] neg_lo:[0,0,1] neg_hi:[0,0,1]
	v_pk_fma_f32 v[72:73], v[4:5], v[72:73], v[82:83] op_sel_hi:[1,0,1]
	s_nop 0
	v_mov_b32_e32 v85, v73
	s_waitcnt vmcnt(0)
	v_pk_add_f32 v[72:73], v[84:85], v[104:105]
	s_nop 0
	v_mov_b32_e32 v0, v73
.Ls5_tail_done:
	s_waitcnt vmcnt(0)
; #define TIDX tid_()
; DEVI unsigned pk_bf16(float lo, float hi) { const bf16x2n r = __builtin_convertvector((f32x2v){lo, hi}, bf16x2n); return __builtin_bit_cast(unsigned, r); }
; DEVI void s5_bfrags(const Params& p, int l, int G, bf16x8 (&bf)[8]) {
;     const int lane = TIDX & 63, l16 = lane & 15, quad = lane >> 4;
;     const float* S5B = (const float*)(p.ws + OFF_S5B);
; #pragma unroll
;     for (int nt = 0; nt < 8; ++nt) {
;         const int n = nt * 16 + l16, pp = n & 63, im = n >> 6;
;         const float* src = S5B + ((size_t)(l * 16 + G) * 64 + pp) * 32 + im * 16 + (quad & 1) * 8;
;         const f32x4 a = *(const f32x4*)src, c = *(const f32x4*)(src + 4);
;         u32x4 v = (u32x4){pk_bf16(a[0], a[1]), pk_bf16(a[2], a[3]), pk_bf16(c[0], c[1]), pk_bf16(c[2], c[3])};
;         if (quad >= 2) v = (u32x4){0u, 0u, 0u, 0u};
;         bf[nt] = __builtin_bit_cast(bf16x8, v);
;     }
; DEVI void s5_pass_b(const Params& p, int l, int witem, unsigned char* wlraw) {
;     ...
;     bf16x8 cf[4];
;     {
;         const float* cre = p.c_re + ((size_t)(l * 16 + G) * 16 + l16) * 64 + quad * 8;
;         const float* cim = p.c_im + ((size_t)(l * 16 + G) * 16 + l16) * 64 + quad * 8;
; #pragma unroll
;         for (int ks = 0; ks < 4; ++ks) {
;             const float* sp = (ks < 2 ? cre : cim) + (ks & 1) * 32;
;             const float sg = ks < 2 ? 1.f : -1.f;
;             const float4 a = *(const float4*)sp, c = *(const float4*)(sp + 4);
;             union { bf16x8 v; unsigned u[4]; } cv;
;             cv.u[0] = pk_bf16(sg * a.x, sg * a.y); cv.u[1] = pk_bf16(sg * a.z, sg * a.w); cv.u[2] = pk_bf16(sg * c.x, sg * c.y); cv.u[3] = pk_bf16(sg * c.z, sg * c.w);
;             cf[ks] = cv.v;
;         }
;     }
;     const float dsk = p.ssm_d[(l * 16 + G) * 16 + l16];
.LBB0_715:
	v_and_b32_e32 v0, 32, v78
	v_cmp_eq_u32_e32 vcc, 0, v0
	v_cvt_pk_bf16_f32 v0, v60, v61
	v_cvt_pk_bf16_f32 v4, v62, v63
	v_cvt_pk_bf16_f32 v5, v52, v53
	v_cvt_pk_bf16_f32 v6, v54, v55
	v_cndmask_b32_e32 v7, 0, v6, vcc
	v_cndmask_b32_e32 v6, 0, v5, vcc
	v_cndmask_b32_e32 v5, 0, v4, vcc
	v_cndmask_b32_e32 v4, 0, v0, vcc
	v_cvt_pk_bf16_f32 v0, v16, v17
	v_cvt_pk_bf16_f32 v16, v18, v19
	v_cvt_pk_bf16_f32 v8, v8, v9
	v_cvt_pk_bf16_f32 v9, v10, v11
	v_cndmask_b32_e32 v11, 0, v9, vcc
	v_cndmask_b32_e32 v10, 0, v8, vcc
	v_cndmask_b32_e32 v9, 0, v16, vcc
	v_cndmask_b32_e32 v8, 0, v0, vcc
	v_cvt_pk_bf16_f32 v0, v44, v45
	v_cvt_pk_bf16_f32 v16, v46, v47
	v_cvt_pk_bf16_f32 v12, v12, v13
	v_cvt_pk_bf16_f32 v13, v14, v15
	v_cndmask_b32_e32 v15, 0, v13, vcc
	v_cndmask_b32_e32 v14, 0, v12, vcc
	v_cndmask_b32_e32 v13, 0, v16, vcc
	v_cndmask_b32_e32 v12, 0, v0, vcc
	v_cvt_pk_bf16_f32 v0, v56, v57
	v_cvt_pk_bf16_f32 v16, v58, v59
	v_cvt_pk_bf16_f32 v17, v64, v65
	v_cvt_pk_bf16_f32 v18, v66, v67
	v_cndmask_b32_e32 v19, 0, v18, vcc
	v_cndmask_b32_e32 v18, 0, v17, vcc
	v_cndmask_b32_e32 v17, 0, v16, vcc
	v_cndmask_b32_e32 v16, 0, v0, vcc
	v_cvt_pk_bf16_f32 v0, v40, v41
	v_cvt_pk_bf16_f32 v20, v20, v21
	v_cvt_pk_bf16_f32 v21, v22, v23
	v_cndmask_b32_e32 v22, 0, v20, vcc
	v_cndmask_b32_e32 v20, 0, v0, vcc
	v_cvt_pk_bf16_f32 v0, v36, v37
	v_cvt_pk_bf16_f32 v24, v24, v25
	v_readlane_b32 s80, v223, 26
	s_lshl_b32 s26, s41, 4
	v_cvt_pk_bf16_f32 v25, v26, v27
	v_cndmask_b32_e32 v26, 0, v24, vcc
	v_cndmask_b32_e32 v24, 0, v0, vcc
	v_cvt_pk_bf16_f32 v0, v28, v29
	v_cvt_pk_bf16_f32 v28, v30, v31
	s_waitcnt vmcnt(1)
	v_cvt_pk_bf16_f32 v29, v68, v69
	v_cvt_pk_bf16_f32 v30, v70, v71
	s_lshl_b64 s[42:43], s[24:25], 12
	v_readlane_b32 s92, v223, 38
	v_and_b32_e32 v74, 15, v77
	v_cndmask_b32_e32 v31, 0, v30, vcc
	v_cndmask_b32_e32 v30, 0, v29, vcc
	v_cndmask_b32_e32 v29, 0, v28, vcc
	v_cndmask_b32_e32 v28, 0, v0, vcc
	v_cvt_pk_bf16_f32 v0, v32, v33
	v_cvt_pk_bf16_f32 v32, v34, v35
	s_waitcnt vmcnt(0)
	v_cvt_pk_bf16_f32 v33, v48, v49
	v_cvt_pk_bf16_f32 v34, v50, v51
	v_readlane_b32 s93, v223, 39
	s_add_u32 s46, s92, s42
	v_lshrrev_b32_e32 v75, 4, v76
	v_cvt_pk_bf16_f32 v36, v38, v39
	v_cndmask_b32_e32 v35, 0, v34, vcc
	v_cndmask_b32_e32 v34, 0, v33, vcc
	v_cndmask_b32_e32 v33, 0, v32, vcc
	v_cndmask_b32_e32 v32, 0, v0, vcc
	v_lshlrev_b32_e32 v0, 8, v74
	s_addc_u32 s47, s93, s43
	v_cndmask_b32_e32 v27, 0, v25, vcc
	v_cndmask_b32_e32 v25, 0, v36, vcc
	v_lshl_add_u64 v[36:37], s[46:47], 0, v[0:1]
	v_lshlrev_b32_e32 v50, 5, v75
	v_mov_b32_e32 v51, v1
	v_cvt_pk_bf16_f32 v40, v42, v43
	v_lshl_add_u64 v[46:47], v[36:37], 0, v[50:51]
	v_cndmask_b32_e32 v23, 0, v21, vcc
	v_cndmask_b32_e32 v21, 0, v40, vcc
	global_load_dwordx4 v[38:41], v[46:47], off offset:16
	global_load_dwordx4 v[42:45], v[46:47], off
	v_readlane_b32 s94, v223, 40
	v_readlane_b32 s95, v223, 41
	s_add_u32 s42, s94, s42
	s_addc_u32 s43, s95, s43
	v_readlane_b32 s64, v223, 0
	v_readlane_b32 s65, v223, 1
	s_mov_b32 s22, 0
	v_readlane_b32 s81, v223, 27
	v_readlane_b32 s82, v223, 28
	v_readlane_b32 s83, v223, 29
	v_readlane_b32 s84, v223, 30
	v_readlane_b32 s85, v223, 31
	v_readlane_b32 s86, v223, 32
	v_readlane_b32 s87, v223, 33
	v_readlane_b32 s88, v223, 34
	v_readlane_b32 s89, v223, 35
	v_readlane_b32 s90, v223, 36
	v_readlane_b32 s91, v223, 37
	v_readlane_b32 s66, v223, 2
	v_readlane_b32 s67, v223, 3
	v_readlane_b32 s68, v223, 4
	v_readlane_b32 s69, v223, 5
	v_readlane_b32 s70, v223, 6
	v_readlane_b32 s71, v223, 7
	v_lshlrev_b32_e32 v65, 2, v75
	v_lshl_add_u32 v66, v76, 1, s39
	v_pk_mov_b32 v[62:63], v[2:3], v[2:3] op_sel:[1,0]
	s_mov_b64 s[94:95], 0
	s_waitcnt vmcnt(1)
	v_cvt_pk_bf16_f32 v38, v38, v39
	s_waitcnt vmcnt(0)
	v_cvt_pk_bf16_f32 v36, v42, v43
	v_cvt_pk_bf16_f32 v37, v44, v45
	global_load_dwordx4 v[42:45], v[46:47], off offset:144
	s_nop 0
	global_load_dwordx4 v[46:49], v[46:47], off offset:128
	v_cvt_pk_bf16_f32 v39, v40, v41
	s_waitcnt vmcnt(1)
	v_cvt_pk_bf16_f32 v42, v42, v43
	v_cvt_pk_bf16_f32 v43, v44, v45
	v_lshl_add_u64 v[44:45], s[42:43], 0, v[0:1]
	v_lshl_add_u64 v[54:55], v[44:45], 0, v[50:51]
	s_waitcnt vmcnt(0)
	v_cvt_pk_bf16_f32 v40, v46, v47
	v_cvt_pk_bf16_f32 v41, v48, v49
	global_load_dwordx4 v[46:49], v[54:55], off offset:16
	global_load_dwordx4 v[50:53], v[54:55], off
	v_and_b32_e32 v0, 48, v76
	s_waitcnt vmcnt(1)
	v_pk_add_f32 v[46:47], v[46:47], 0 neg_lo:[1,1] neg_hi:[1,1]
	s_waitcnt vmcnt(0)
	v_pk_add_f32 v[44:45], v[50:51], 0 neg_lo:[1,1] neg_hi:[1,1]
	v_pk_add_f32 v[50:51], v[52:53], 0 neg_lo:[1,1] neg_hi:[1,1]
	v_cvt_pk_bf16_f32 v44, v44, v45
	v_cvt_pk_bf16_f32 v45, v50, v51
	global_load_dwordx4 v[50:53], v[54:55], off offset:144
	s_nop 0
	global_load_dwordx4 v[54:57], v[54:55], off offset:128
	v_pk_add_f32 v[48:49], v[48:49], 0 neg_lo:[1,1] neg_hi:[1,1]
	v_cvt_pk_bf16_f32 v46, v46, v47
	v_cvt_pk_bf16_f32 v47, v48, v49
	s_waitcnt vmcnt(1)
	v_pk_add_f32 v[50:51], v[50:51], 0 neg_lo:[1,1] neg_hi:[1,1]
	v_pk_add_f32 v[52:53], v[52:53], 0 neg_lo:[1,1] neg_hi:[1,1]
	v_cvt_pk_bf16_f32 v50, v50, v51
	v_cvt_pk_bf16_f32 v51, v52, v53
	v_lshl_or_b32 v52, s24, 4, v74
	v_ashrrev_i32_e32 v53, 31, v52
	v_lshl_add_u64 v[52:53], v[52:53], 2, s[64:65]
	global_load_dword v64, v[52:53], off
	s_lshl_b32 s24, s26, 1
	s_add_u32 s24, s11, s24
	s_waitcnt vmcnt(1)
	v_pk_add_f32 v[48:49], v[54:55], 0 neg_lo:[1,1] neg_hi:[1,1]
	v_pk_add_f32 v[54:55], v[56:57], 0 neg_lo:[1,1] neg_hi:[1,1]
	v_add_u32_e32 v52, s39, v0
	s_addc_u32 s25, s13, 0
	v_lshlrev_b32_e32 v0, 1, v74
	v_mul_u32_u24_e32 v53, 0x110, v74
	v_cvt_pk_bf16_f32 v48, v48, v49
	v_cvt_pk_bf16_f32 v49, v54, v55
	v_lshl_add_u64 v[60:61], s[24:25], 0, v[0:1]
	v_lshl_add_u32 v0, v74, 2, s39
	s_mov_b64 s[26:27], -1
	v_add_u32_e32 v67, v52, v53
	s_waitcnt vmcnt(0)

; DEVI void phase_gemm_res(const Params& p, const bf16_t* A, int K, const bf16_t* Bt, const float* xraw, int lnidx, float bscale, bf16_t* smem) {
;     ...
;             f32x4 g4[4], b4[4];
; #pragma unroll
;             for (int ni = 0; ni < 4; ++ni) {
;                 const int col = tn * 128 + wc * 64 + ni * 16 + quad * 4;
;                 g4[ni] = *(const f32x4*)(lg + col) * ALPHA; b4[ni] = *(const f32x4*)(lb + col) * ALPHA;
;             }
; #pragma unroll
;             for (int mi = 0; mi < 4; ++mi) {
;                 const int row = tm * 128 + wr * 64 + mi * 16 + l16;
;                 const f32x2v st = stats[row];
; #pragma unroll
;                 for (int ni = 0; ni < 4; ++ni) {
;                     const size_t idx = (size_t)row * D_ + tn * 128 + wc * 64 + ni * 16 + quad * 4;
;                     const f32x4 rv = *(const f32x4*)(hbuf + idx);
;                     *(f32x4*)(hbuf + idx) = ((rv - st[0]) * st[1]) * g4[ni] + b4[ni] + acc[mi][ni] * bscale;
;                 }
;             }
.LBB0_775:
	s_lshl_b32 s38, s43, 7
	s_ashr_i32 s39, s38, 31
	v_or_b32_e32 v210, s38, v66
	v_ashrrev_i32_e32 v211, 31, v210
	v_lshlrev_b64 v[210:211], 2, v[210:211]
	v_lshl_add_u64 v[206:207], s[24:25], 0, v[210:211]
	v_lshl_add_u64 v[208:209], s[26:27], 0, v[210:211]
	v_ashrrev_i32_e32 v71, 31, v70
	global_load_dwordx4 v[72:75], v[206:207], off
	global_load_dwordx4 v[76:79], v[206:207], off offset:64
	global_load_dwordx4 v[80:83], v[206:207], off offset:128
	global_load_dwordx4 v[84:87], v[206:207], off offset:192
	global_load_dwordx4 v[88:91], v[208:209], off
	global_load_dwordx4 v[92:95], v[208:209], off offset:64
	global_load_dwordx4 v[96:99], v[208:209], off offset:128
	global_load_dwordx4 v[100:103], v[208:209], off offset:192
	v_lshl_add_u64 v[210:211], v[70:71], 3, s[14:15]
	global_load_dwordx2 v[106:107], v[210:211], off
	global_load_dwordx2 v[108:109], v[210:211], off offset:128
	global_load_dwordx2 v[110:111], v[210:211], off offset:256
	global_load_dwordx2 v[140:141], v[210:211], off offset:384
	v_lshl_add_u64 v[212:213], s[38:39], 2, v[68:69]
	v_lshlrev_b64 v[214:215], 12, v[70:71]
	v_lshl_add_u64 v[128:129], v[212:213], 0, v[214:215]
	s_mov_b64 s[38:39], 0x10000
	v_lshl_add_u64 v[130:131], v[128:129], 0, s[38:39]
	v_lshl_add_u64 v[134:135], v[130:131], 0, s[38:39]
	v_lshl_add_u64 v[138:139], v[134:135], 0, s[38:39]
	global_load_dwordx4 v[112:115], v[128:129], off
	global_load_dwordx4 v[116:119], v[128:129], off offset:64
	global_load_dwordx4 v[120:123], v[128:129], off offset:128
	global_load_dwordx4 v[124:127], v[128:129], off offset:192
	global_load_dwordx4 v[160:163], v[130:131], off
	global_load_dwordx4 v[164:167], v[130:131], off offset:64
	global_load_dwordx4 v[168:171], v[130:131], off offset:128
	global_load_dwordx4 v[172:175], v[130:131], off offset:192
	global_load_dwordx4 v[176:179], v[134:135], off
	global_load_dwordx4 v[180:183], v[134:135], off offset:64
	global_load_dwordx4 v[184:187], v[134:135], off offset:128
	global_load_dwordx4 v[188:191], v[134:135], off offset:192
	global_load_dwordx4 v[192:195], v[138:139], off
	global_load_dwordx4 v[196:199], v[138:139], off offset:64
	global_load_dwordx4 v[200:203], v[138:139], off offset:128
	global_load_dwordx4 v[216:219], v[138:139], off offset:192
	s_waitcnt vmcnt(16)
	v_pk_mul_f32 v[72:73], v[72:73], s[20:21] op_sel_hi:[1,0]
	v_pk_mul_f32 v[74:75], v[74:75], s[20:21] op_sel_hi:[1,0]
	v_pk_mul_f32 v[88:89], v[88:89], s[20:21] op_sel_hi:[1,0]
	v_pk_mul_f32 v[90:91], v[90:91], s[20:21] op_sel_hi:[1,0]
	v_pk_mul_f32 v[76:77], v[76:77], s[20:21] op_sel_hi:[1,0]
	v_pk_mul_f32 v[78:79], v[78:79], s[20:21] op_sel_hi:[1,0]
	v_pk_mul_f32 v[92:93], v[92:93], s[20:21] op_sel_hi:[1,0]
	v_pk_mul_f32 v[94:95], v[94:95], s[20:21] op_sel_hi:[1,0]
	v_pk_mul_f32 v[80:81], v[80:81], s[20:21] op_sel_hi:[1,0]
	v_pk_mul_f32 v[82:83], v[82:83], s[20:21] op_sel_hi:[1,0]
	v_pk_mul_f32 v[96:97], v[96:97], s[20:21] op_sel_hi:[1,0]
	v_pk_mul_f32 v[98:99], v[98:99], s[20:21] op_sel_hi:[1,0]
	v_pk_mul_f32 v[84:85], v[84:85], s[20:21] op_sel_hi:[1,0]
	v_pk_mul_f32 v[86:87], v[86:87], s[20:21] op_sel_hi:[1,0]
	v_pk_mul_f32 v[100:101], v[100:101], s[20:21] op_sel_hi:[1,0]
	v_pk_mul_f32 v[102:103], v[102:103], s[20:21] op_sel_hi:[1,0]
	s_waitcnt vmcnt(15)
	v_sub_f32_e32 v113, v113, v106
	v_sub_f32_e32 v112, v112, v106
	v_sub_f32_e32 v115, v115, v106
	v_sub_f32_e32 v114, v114, v106
	v_pk_mul_f32 v[114:115], v[106:107], v[114:115] op_sel:[1,0]
	v_pk_mul_f32 v[112:113], v[106:107], v[112:113] op_sel:[1,0]
	v_pk_fma_f32 v[114:115], v[74:75], v[114:115], v[90:91]
	v_pk_fma_f32 v[112:113], v[72:73], v[112:113], v[88:89]
	v_pk_fma_f32 v[64:65], v[64:65], 0.5, v[114:115] op_sel_hi:[1,0,1]
	v_pk_fma_f32 v[62:63], v[62:63], 0.5, v[112:113] op_sel_hi:[1,0,1]
	global_store_dwordx4 v[128:129], v[62:65], off
	s_waitcnt vmcnt(15)
	v_sub_f32_e32 v117, v117, v106
	v_sub_f32_e32 v116, v116, v106
	v_sub_f32_e32 v119, v119, v106
	v_sub_f32_e32 v118, v118, v106
	v_pk_mul_f32 v[118:119], v[106:107], v[118:119] op_sel:[1,0]
	v_pk_mul_f32 v[116:117], v[106:107], v[116:117] op_sel:[1,0]
	v_pk_fma_f32 v[118:119], v[78:79], v[118:119], v[94:95]
	v_pk_fma_f32 v[116:117], v[76:77], v[116:117], v[92:93]
	v_pk_fma_f32 v[60:61], v[60:61], 0.5, v[118:119] op_sel_hi:[1,0,1]
	v_pk_fma_f32 v[58:59], v[58:59], 0.5, v[116:117] op_sel_hi:[1,0,1]
	global_store_dwordx4 v[128:129], v[58:61], off offset:64
	s_waitcnt vmcnt(15)
	v_sub_f32_e32 v121, v121, v106
	v_sub_f32_e32 v120, v120, v106
	v_sub_f32_e32 v123, v123, v106
	v_sub_f32_e32 v122, v122, v106
	v_pk_mul_f32 v[122:123], v[106:107], v[122:123] op_sel:[1,0]
	v_pk_mul_f32 v[120:121], v[106:107], v[120:121] op_sel:[1,0]
	v_pk_fma_f32 v[122:123], v[82:83], v[122:123], v[98:99]
	v_pk_fma_f32 v[120:121], v[80:81], v[120:121], v[96:97]
	v_pk_fma_f32 v[56:57], v[56:57], 0.5, v[122:123] op_sel_hi:[1,0,1]
	v_pk_fma_f32 v[54:55], v[54:55], 0.5, v[120:121] op_sel_hi:[1,0,1]
	global_store_dwordx4 v[128:129], v[54:57], off offset:128
	s_waitcnt vmcnt(15)
	v_sub_f32_e32 v125, v125, v106
	v_sub_f32_e32 v124, v124, v106
	v_sub_f32_e32 v127, v127, v106
	v_sub_f32_e32 v126, v126, v106
	v_pk_mul_f32 v[126:127], v[106:107], v[126:127] op_sel:[1,0]
	v_pk_mul_f32 v[124:125], v[106:107], v[124:125] op_sel:[1,0]
	v_pk_fma_f32 v[126:127], v[86:87], v[126:127], v[102:103]
	v_pk_fma_f32 v[124:125], v[84:85], v[124:125], v[100:101]
	v_pk_fma_f32 v[52:53], v[52:53], 0.5, v[126:127] op_sel_hi:[1,0,1]
	v_pk_fma_f32 v[50:51], v[50:51], 0.5, v[124:125] op_sel_hi:[1,0,1]
	global_store_dwordx4 v[128:129], v[50:53], off offset:192
	s_waitcnt vmcnt(15)
; DEVI void phase_gemm_res(const Params& p, const bf16_t* A, int K, const bf16_t* Bt, const float* xraw, int lnidx, float bscale, bf16_t* smem) {
;     ...
; #pragma unroll
;             for (int mi = 0; mi < 4; ++mi) {
;                 const int row = tm * 128 + wr * 64 + mi * 16 + l16;
;                 const f32x2v st = stats[row];
; #pragma unroll
;                 for (int ni = 0; ni < 4; ++ni) {
;                     const size_t idx = (size_t)row * D_ + tn * 128 + wc * 64 + ni * 16 + quad * 4;
;                     const f32x4 rv = *(const f32x4*)(hbuf + idx);
;                     *(f32x4*)(hbuf + idx) = ((rv - st[0]) * st[1]) * g4[ni] + b4[ni] + acc[mi][ni] * bscale;
;                 }
;             }
	v_sub_f32_e32 v161, v161, v108
	v_sub_f32_e32 v160, v160, v108
	v_sub_f32_e32 v163, v163, v108
	v_sub_f32_e32 v162, v162, v108
	v_pk_mul_f32 v[162:163], v[108:109], v[162:163] op_sel:[1,0]
	v_pk_mul_f32 v[160:161], v[108:109], v[160:161] op_sel:[1,0]
	v_pk_fma_f32 v[162:163], v[74:75], v[162:163], v[90:91]
	v_pk_fma_f32 v[160:161], v[72:73], v[160:161], v[88:89]
	v_pk_fma_f32 v[48:49], v[48:49], 0.5, v[162:163] op_sel_hi:[1,0,1]
	v_pk_fma_f32 v[46:47], v[46:47], 0.5, v[160:161] op_sel_hi:[1,0,1]
	global_store_dwordx4 v[130:131], v[46:49], off
	s_waitcnt vmcnt(15)
	v_sub_f32_e32 v165, v165, v108
	v_sub_f32_e32 v164, v164, v108
	v_sub_f32_e32 v167, v167, v108
	v_sub_f32_e32 v166, v166, v108
	v_pk_mul_f32 v[166:167], v[108:109], v[166:167] op_sel:[1,0]
	v_pk_mul_f32 v[164:165], v[108:109], v[164:165] op_sel:[1,0]
	v_pk_fma_f32 v[166:167], v[78:79], v[166:167], v[94:95]
	v_pk_fma_f32 v[164:165], v[76:77], v[164:165], v[92:93]
	v_pk_fma_f32 v[44:45], v[44:45], 0.5, v[166:167] op_sel_hi:[1,0,1]
	v_pk_fma_f32 v[42:43], v[42:43], 0.5, v[164:165] op_sel_hi:[1,0,1]
	global_store_dwordx4 v[130:131], v[42:45], off offset:64
	s_waitcnt vmcnt(15)
	v_sub_f32_e32 v169, v169, v108
	v_sub_f32_e32 v168, v168, v108
	v_sub_f32_e32 v171, v171, v108
	v_sub_f32_e32 v170, v170, v108
	v_pk_mul_f32 v[170:171], v[108:109], v[170:171] op_sel:[1,0]
	v_pk_mul_f32 v[168:169], v[108:109], v[168:169] op_sel:[1,0]
	v_pk_fma_f32 v[170:171], v[82:83], v[170:171], v[98:99]
	v_pk_fma_f32 v[168:169], v[80:81], v[168:169], v[96:97]
	v_pk_fma_f32 v[40:41], v[40:41], 0.5, v[170:171] op_sel_hi:[1,0,1]
	v_pk_fma_f32 v[38:39], v[38:39], 0.5, v[168:169] op_sel_hi:[1,0,1]
	global_store_dwordx4 v[130:131], v[38:41], off offset:128
	s_waitcnt vmcnt(15)
	v_sub_f32_e32 v173, v173, v108
	v_sub_f32_e32 v172, v172, v108
	v_sub_f32_e32 v175, v175, v108
	v_sub_f32_e32 v174, v174, v108
	v_pk_mul_f32 v[174:175], v[108:109], v[174:175] op_sel:[1,0]
	v_pk_mul_f32 v[172:173], v[108:109], v[172:173] op_sel:[1,0]
	v_pk_fma_f32 v[174:175], v[86:87], v[174:175], v[102:103]
	v_pk_fma_f32 v[172:173], v[84:85], v[172:173], v[100:101]
	v_pk_fma_f32 v[36:37], v[36:37], 0.5, v[174:175] op_sel_hi:[1,0,1]
	v_pk_fma_f32 v[34:35], v[34:35], 0.5, v[172:173] op_sel_hi:[1,0,1]
	global_store_dwordx4 v[130:131], v[34:37], off offset:192
	s_waitcnt vmcnt(15)
	v_sub_f32_e32 v177, v177, v110
	v_sub_f32_e32 v176, v176, v110
	v_sub_f32_e32 v179, v179, v110
	v_sub_f32_e32 v178, v178, v110
	v_pk_mul_f32 v[178:179], v[110:111], v[178:179] op_sel:[1,0]
	v_pk_mul_f32 v[176:177], v[110:111], v[176:177] op_sel:[1,0]
	v_pk_fma_f32 v[178:179], v[74:75], v[178:179], v[90:91]
	v_pk_fma_f32 v[176:177], v[72:73], v[176:177], v[88:89]
	v_pk_fma_f32 v[32:33], v[32:33], 0.5, v[178:179] op_sel_hi:[1,0,1]
	v_pk_fma_f32 v[30:31], v[30:31], 0.5, v[176:177] op_sel_hi:[1,0,1]
	global_store_dwordx4 v[134:135], v[30:33], off
	s_waitcnt vmcnt(15)
	v_sub_f32_e32 v181, v181, v110
	v_sub_f32_e32 v180, v180, v110
	v_sub_f32_e32 v183, v183, v110
	v_sub_f32_e32 v182, v182, v110
	v_pk_mul_f32 v[182:183], v[110:111], v[182:183] op_sel:[1,0]
	v_pk_mul_f32 v[180:181], v[110:111], v[180:181] op_sel:[1,0]
	v_pk_fma_f32 v[182:183], v[78:79], v[182:183], v[94:95]
	v_pk_fma_f32 v[180:181], v[76:77], v[180:181], v[92:93]
	v_pk_fma_f32 v[28:29], v[28:29], 0.5, v[182:183] op_sel_hi:[1,0,1]
	v_pk_fma_f32 v[26:27], v[26:27], 0.5, v[180:181] op_sel_hi:[1,0,1]
	global_store_dwordx4 v[134:135], v[26:29], off offset:64
	s_waitcnt vmcnt(15)
	v_sub_f32_e32 v185, v185, v110
	v_sub_f32_e32 v184, v184, v110
	v_sub_f32_e32 v187, v187, v110
	v_sub_f32_e32 v186, v186, v110
	v_pk_mul_f32 v[186:187], v[110:111], v[186:187] op_sel:[1,0]
	v_pk_mul_f32 v[184:185], v[110:111], v[184:185] op_sel:[1,0]
	v_pk_fma_f32 v[186:187], v[82:83], v[186:187], v[98:99]
	v_pk_fma_f32 v[184:185], v[80:81], v[184:185], v[96:97]
	v_pk_fma_f32 v[24:25], v[24:25], 0.5, v[186:187] op_sel_hi:[1,0,1]
	v_pk_fma_f32 v[22:23], v[22:23], 0.5, v[184:185] op_sel_hi:[1,0,1]
	global_store_dwordx4 v[134:135], v[22:25], off offset:128
	s_waitcnt vmcnt(15)
	v_sub_f32_e32 v189, v189, v110
	v_sub_f32_e32 v188, v188, v110
	v_sub_f32_e32 v191, v191, v110
	v_sub_f32_e32 v190, v190, v110
	v_pk_mul_f32 v[190:191], v[110:111], v[190:191] op_sel:[1,0]
	v_pk_mul_f32 v[188:189], v[110:111], v[188:189] op_sel:[1,0]
	v_pk_fma_f32 v[190:191], v[86:87], v[190:191], v[102:103]
	v_pk_fma_f32 v[188:189], v[84:85], v[188:189], v[100:101]
	v_pk_fma_f32 v[20:21], v[20:21], 0.5, v[190:191] op_sel_hi:[1,0,1]
	v_pk_fma_f32 v[18:19], v[18:19], 0.5, v[188:189] op_sel_hi:[1,0,1]
	global_store_dwordx4 v[134:135], v[18:21], off offset:192
	s_waitcnt vmcnt(15)
	v_sub_f32_e32 v193, v193, v140
	v_sub_f32_e32 v192, v192, v140
	v_sub_f32_e32 v195, v195, v140
	v_sub_f32_e32 v194, v194, v140
	v_pk_mul_f32 v[194:195], v[140:141], v[194:195] op_sel:[1,0]
	v_pk_mul_f32 v[192:193], v[140:141], v[192:193] op_sel:[1,0]
	v_pk_fma_f32 v[194:195], v[74:75], v[194:195], v[90:91]
	v_pk_fma_f32 v[192:193], v[72:73], v[192:193], v[88:89]
	v_pk_fma_f32 v[16:17], v[16:17], 0.5, v[194:195] op_sel_hi:[1,0,1]
	v_pk_fma_f32 v[14:15], v[14:15], 0.5, v[192:193] op_sel_hi:[1,0,1]
	global_store_dwordx4 v[138:139], v[14:17], off
	s_waitcnt vmcnt(15)
	v_sub_f32_e32 v197, v197, v140
	v_sub_f32_e32 v196, v196, v140
	v_sub_f32_e32 v199, v199, v140
	v_sub_f32_e32 v198, v198, v140
	v_pk_mul_f32 v[198:199], v[140:141], v[198:199] op_sel:[1,0]
	v_pk_mul_f32 v[196:197], v[140:141], v[196:197] op_sel:[1,0]
	v_pk_fma_f32 v[198:199], v[78:79], v[198:199], v[94:95]
	v_pk_fma_f32 v[196:197], v[76:77], v[196:197], v[92:93]
	v_pk_fma_f32 v[8:9], v[8:9], 0.5, v[198:199] op_sel_hi:[1,0,1]
	v_pk_fma_f32 v[6:7], v[6:7], 0.5, v[196:197] op_sel_hi:[1,0,1]
	global_store_dwordx4 v[138:139], v[6:9], off offset:64
	s_waitcnt vmcnt(15)
	v_sub_f32_e32 v201, v201, v140
	v_sub_f32_e32 v200, v200, v140
	v_sub_f32_e32 v203, v203, v140
	v_sub_f32_e32 v202, v202, v140
	v_pk_mul_f32 v[202:203], v[140:141], v[202:203] op_sel:[1,0]
	v_pk_mul_f32 v[200:201], v[140:141], v[200:201] op_sel:[1,0]
	v_pk_fma_f32 v[202:203], v[82:83], v[202:203], v[98:99]
	v_pk_fma_f32 v[200:201], v[80:81], v[200:201], v[96:97]
	v_pk_fma_f32 v[12:13], v[12:13], 0.5, v[202:203] op_sel_hi:[1,0,1]
	v_pk_fma_f32 v[10:11], v[10:11], 0.5, v[200:201] op_sel_hi:[1,0,1]
	global_store_dwordx4 v[138:139], v[10:13], off offset:128
	s_waitcnt vmcnt(15)
	v_sub_f32_e32 v217, v217, v140
	v_sub_f32_e32 v216, v216, v140
	v_sub_f32_e32 v219, v219, v140
	v_sub_f32_e32 v218, v218, v140
	v_pk_mul_f32 v[218:219], v[140:141], v[218:219] op_sel:[1,0]
	v_pk_mul_f32 v[216:217], v[140:141], v[216:217] op_sel:[1,0]
	v_pk_fma_f32 v[218:219], v[86:87], v[218:219], v[102:103]
	v_pk_fma_f32 v[216:217], v[84:85], v[216:217], v[100:101]
	v_pk_fma_f32 v[4:5], v[4:5], 0.5, v[218:219] op_sel_hi:[1,0,1]
	v_pk_fma_f32 v[2:3], v[2:3], 0.5, v[216:217] op_sel_hi:[1,0,1]
	global_store_dwordx4 v[138:139], v[2:5], off offset:192
	s_branch .LBB0_755

; DEVI void phase_prologue(const Params& p, unsigned char* smem_raw) {
;     ...
;         } else if (item < NT_W + NHB + NCS + NCB) {
;             const int it = item - NT_W - NHB - NCS;
;             const int job = it >> 3, sl = it & 7, l = job >> 1, kv = job & 1;
;             const float* pe = (kv ? p.pe_v : p.pe_k) + (size_t)l * 2048;
;             const float* w1 = (kv ? p.cv_w1 : p.ck_w1) + (size_t)l * 2048 * 128;
;             const int n = tid & 127, half = tid >> 7;
;             float s = 0.f;
;             const int k0 = sl * 256 + half * 128;
; #pragma unroll 16
;             for (int k = k0; k < k0 + 128; ++k) s += pe[k] * w1[(size_t)k * 128 + n];
;             __syncthreads();
;             if (half) tl[n] = s;
;             __syncthreads();
;             if (!half) ((float*)(ws + OFF_CBIAS))[it * 128 + n] = s + tl[n];
;             __syncthreads();
.LBB0_818:
	s_movk_i32 s6, 0xf000
	v_add_co_u32_e32 v16, vcc, s6, v2
	global_load_dwordx4 v[8:11], v[4:5], off offset:-12
	global_load_dwordx4 v[12:15], v[4:5], off offset:-28
	global_load_dwordx4 v[28:31], v[4:5], off offset:-44
	global_load_dwordx4 v[40:43], v[4:5], off offset:-60
	v_addc_co_u32_e32 v17, vcc, -1, v3, vcc
	global_load_dword v60, v[16:17], off offset:-3584
	global_load_dword v61, v[16:17], off offset:-3072
	global_load_dword v62, v[16:17], off offset:-2560
	global_load_dword v63, v[16:17], off offset:-2048
	global_load_dword v64, v[16:17], off offset:-1536
	global_load_dword v65, v[16:17], off offset:-1024
	global_load_dword v66, v[16:17], off offset:-512
	global_load_dword v67, v[2:3], off offset:-4096
	global_load_dword v68, v[2:3], off offset:-3584
	global_load_dword v69, v[2:3], off offset:-3072
	global_load_dword v70, v[2:3], off offset:-2560
	global_load_dword v71, v[2:3], off offset:-2048
	global_load_dword v72, v[2:3], off offset:-1536
	global_load_dword v73, v[2:3], off offset:-1024
	global_load_dword v74, v[2:3], off offset:-512
	global_load_dword v75, v[2:3], off
	v_add_u32_e32 v7, 16, v7
	v_cmp_ge_i32_e32 vcc, v7, v0
	v_lshl_add_u64 v[4:5], v[4:5], 0, 64
	s_or_b64 s[0:1], vcc, s[0:1]
	v_lshl_add_u64 v[2:3], v[2:3], 0, s[36:37]
	s_waitcnt vmcnt(15)
	v_fmac_f32_e32 v6, v40, v60
	s_waitcnt vmcnt(14)
	v_fmac_f32_e32 v6, v41, v61
	s_waitcnt vmcnt(13)
	v_fmac_f32_e32 v6, v42, v62
	s_waitcnt vmcnt(12)
	v_fmac_f32_e32 v6, v43, v63
	s_waitcnt vmcnt(11)
	v_fmac_f32_e32 v6, v28, v64
	s_waitcnt vmcnt(10)
	v_fmac_f32_e32 v6, v29, v65
	s_waitcnt vmcnt(9)
	v_fmac_f32_e32 v6, v30, v66
	s_waitcnt vmcnt(8)
	v_fmac_f32_e32 v6, v31, v67
	s_waitcnt vmcnt(7)
	v_fmac_f32_e32 v6, v12, v68
	s_waitcnt vmcnt(6)
	v_fmac_f32_e32 v6, v13, v69
	s_waitcnt vmcnt(5)
	v_fmac_f32_e32 v6, v14, v70
	s_waitcnt vmcnt(4)
	v_fmac_f32_e32 v6, v15, v71
	s_waitcnt vmcnt(3)
	v_fmac_f32_e32 v6, v8, v72
	s_waitcnt vmcnt(2)
	v_fmac_f32_e32 v6, v9, v73
	s_waitcnt vmcnt(1)
	v_fmac_f32_e32 v6, v10, v74
	s_waitcnt vmcnt(0)
	v_fmac_f32_e32 v6, v11, v75
	s_andn2_b64 exec, exec, s[0:1]
	s_cbranch_execnz .LBB0_818
	s_or_b64 exec, exec, s[0:1]
	s_barrier
	s_and_saveexec_b64 s[0:1], s[14:15]
	ds_write_b32 v18, v6
	s_or_b64 exec, exec, s[0:1]
	s_waitcnt lgkmcnt(0)
	s_barrier
	s_and_saveexec_b64 s[0:1], s[10:11]
	s_cbranch_execz .LBB0_823
	ds_read_b32 v4, v18
	v_readlane_b32 s2, v220, 3
	v_lshl_or_b32 v0, s4, 7, v34
	v_readlane_b32 s3, v220, 4
	s_nop 1
	v_lshl_add_u64 v[2:3], v[0:1], 2, s[2:3]
	s_waitcnt lgkmcnt(0)
	v_add_f32_e32 v0, v6, v4
	global_store_dword v[2:3], v0, off

; DEVI unsigned pk_bf16(float lo, float hi) { const bf16x2n r = __builtin_convertvector((f32x2v){lo, hi}, bf16x2n); return __builtin_bit_cast(unsigned, r); }
; DEVI void phase_prologue(const Params& p, unsigned char* smem_raw) {
;     ...
;         } else if (item < NT_W + NHB) {
;             const int it = item - NT_W;
;             const float* src = p.x + (size_t)it * 8192;
;             bf16_t* dst = (bf16_t*)(ws + OFF_HB) + (size_t)it * 8192;
; #pragma unroll
;             for (int i = 0; i < 4; ++i) {
;                 const int e = (i * 256 + tid) * 8;
;                 const float4 a = *(const float4*)(src + e), b = *(const float4*)(src + e + 4);
;                 uint4 o; o.x = pk_bf16(a.x, a.y); o.y = pk_bf16(a.z, a.w); o.z = pk_bf16(b.x, b.y); o.w = pk_bf16(b.z, b.w);
;                 *(uint4*)(dst + e) = o;
;             }
.LBB0_828:
	s_andn2_b64 vcc, exec, s[0:1]
	s_cbranch_vccnz .LBB0_830
	s_add_i32 s22, s46, 0xffffb040
	s_lshl_b64 s[0:1], s[22:23], 15
	v_readlane_b32 s80, v223, 62
	v_readlane_b32 s81, v223, 63
	s_add_u32 s34, s80, s0
	s_addc_u32 s35, s81, s1
	v_lshl_add_u64 v[52:53], v[20:21], 2, s[34:35]
	v_lshl_add_u64 v[54:55], v[22:23], 2, s[34:35]
	v_lshl_add_u64 v[56:57], v[24:25], 2, s[34:35]
	v_lshl_add_u64 v[58:59], v[26:27], 2, s[34:35]
	global_load_dwordx4 v[60:63], v[52:53], off offset:16
	global_load_dwordx4 v[64:67], v[52:53], off
	global_load_dwordx4 v[68:71], v[54:55], off offset:16
	global_load_dwordx4 v[72:75], v[54:55], off
	global_load_dwordx4 v[76:79], v[56:57], off offset:16
	global_load_dwordx4 v[80:83], v[56:57], off
	global_load_dwordx4 v[84:87], v[58:59], off offset:16
	global_load_dwordx4 v[88:91], v[58:59], off
	s_lshl_b64 s[0:1], s[22:23], 14
	s_add_u32 s0, s13, s0
	s_addc_u32 s1, s17, s1
	v_readlane_b32 s82, v222, 0
	v_readlane_b32 s83, v222, 1
	v_readlane_b32 s84, v222, 2
	v_readlane_b32 s85, v222, 3
	v_readlane_b32 s86, v222, 4
	v_readlane_b32 s87, v222, 5
	v_readlane_b32 s88, v222, 6
	v_readlane_b32 s89, v222, 7
	v_readlane_b32 s90, v222, 8
	v_readlane_b32 s91, v222, 9
	v_readlane_b32 s92, v222, 10
	v_readlane_b32 s93, v222, 11
	v_readlane_b32 s94, v222, 12
	v_readlane_b32 s95, v222, 13
	s_waitcnt vmcnt(6)
	v_cvt_pk_bf16_f32 v92, v64, v65
	v_cvt_pk_bf16_f32 v93, v66, v67
	v_cvt_pk_bf16_f32 v94, v60, v61
	v_cvt_pk_bf16_f32 v95, v62, v63
	v_lshl_add_u64 v[2:3], v[20:21], 1, s[0:1]
	global_store_dwordx4 v[2:3], v[92:95], off
	s_waitcnt vmcnt(5)
	v_cvt_pk_bf16_f32 v96, v72, v73
	v_cvt_pk_bf16_f32 v97, v74, v75
	v_cvt_pk_bf16_f32 v98, v68, v69
	v_cvt_pk_bf16_f32 v99, v70, v71
	v_lshl_add_u64 v[2:3], v[22:23], 1, s[0:1]
	global_store_dwordx4 v[2:3], v[96:99], off
	s_waitcnt vmcnt(4)
	v_cvt_pk_bf16_f32 v100, v80, v81
	v_cvt_pk_bf16_f32 v101, v82, v83
	v_cvt_pk_bf16_f32 v102, v76, v77
	v_cvt_pk_bf16_f32 v103, v78, v79
	v_lshl_add_u64 v[2:3], v[24:25], 1, s[0:1]
	global_store_dwordx4 v[2:3], v[100:103], off
	s_waitcnt vmcnt(3)
	v_cvt_pk_bf16_f32 v104, v88, v89
	v_cvt_pk_bf16_f32 v105, v90, v91
	v_cvt_pk_bf16_f32 v106, v84, v85
	v_cvt_pk_bf16_f32 v107, v86, v87
	v_lshl_add_u64 v[2:3], v[26:27], 1, s[0:1]
	global_store_dwordx4 v[2:3], v[104:107], off
